# GEMM K-loops on v_mfma_f32_16x16x32_bf16 with in-place layout conversion (one barrier per K-step)
# speedup vs baseline: 1.0151x; 1.0151x over previous
.LBB0_71:
	s_ashr_i32 s36, s31, 2
	s_and_b32 s36, s36, -8
	s_or_b32 s36, s36, s3
	s_ashr_i32 s37, s36, 31
	s_lshr_b32 s37, s37, 29
	s_add_i32 s37, s36, s37
	s_ashr_i32 s43, s37, 3
	s_and_b32 s37, s37, 0x1ffff8
	s_bfe_u32 s5, s31, 0x20003
	s_sub_i32 s42, s36, s37
	s_lshl_b32 s37, s43, 2
	s_lshl_b32 s33, s5, 8
	s_or_b32 s37, s37, s5
	s_lshl_b32 s5, s42, 11
	s_lshl_b32 s42, s31, 8
	s_and_b32 s42, s42, 0x700
	s_or_b32 s42, s5, s42
	v_add_u32_e32 v0, s42, v187
	v_ashrrev_i32_e32 v1, 31, v0
	v_lshl_add_u32 v2, s37, 8, v187
	v_lshlrev_b64 v[0:1], 12, v[0:1]
	v_ashrrev_i32_e32 v3, 31, v2
	v_readfirstlane_b32 s5, v188
	v_lshl_add_u64 v[0:1], v[146:147], 0, v[0:1]
	v_lshlrev_b64 v[2:3], 12, v[2:3]
	s_add_i32 m0, s5, -16
	v_readfirstlane_b32 s5, v200
	v_lshl_add_u64 v[2:3], v[148:149], 0, v[2:3]
	global_load_lds_dwordx4 v[0:1], off
	s_add_i32 m0, s5, -16
	v_readfirstlane_b32 s5, v201
	global_load_lds_dwordx4 v[2:3], off
	v_lshl_add_u64 v[4:5], v[0:1], 0, s[6:7]
	s_add_i32 m0, s5, -16
	v_readfirstlane_b32 s5, v202
	global_load_lds_dwordx4 v[4:5], off
	v_lshl_add_u64 v[4:5], v[2:3], 0, s[6:7]
	s_add_i32 m0, s5, -16
	v_readfirstlane_b32 s5, v203
	global_load_lds_dwordx4 v[4:5], off
	v_lshl_add_u64 v[4:5], v[0:1], 0, s[14:15]
	s_add_i32 m0, s5, -16
	v_readfirstlane_b32 s5, v204
	global_load_lds_dwordx4 v[4:5], off
	v_lshl_add_u64 v[4:5], v[2:3], 0, s[14:15]
	s_add_i32 m0, s5, -16
	v_readfirstlane_b32 s5, v205
	global_load_lds_dwordx4 v[4:5], off
	v_lshl_add_u64 v[0:1], v[0:1], 0, s[20:21]
	s_add_i32 m0, s5, -16
	v_readfirstlane_b32 s5, v206
	global_load_lds_dwordx4 v[0:1], off
	v_lshl_add_u64 v[0:1], v[2:3], 0, s[20:21]
	s_add_i32 m0, s5, -16
	s_and_b32 s4, s35, 0x700
	global_load_lds_dwordx4 v[0:1], off
	s_lshl_b32 s5, s36, 11
	s_or_b32 s4, s4, s5
	v_add_u32_e32 v0, s4, v187
	s_lshl_b32 s4, s43, 14
	v_subrev_u32_e32 v0, s4, v0
	v_ashrrev_i32_e32 v1, 31, v0
	s_lshl_b32 s4, s43, 10
	v_lshlrev_b64 v[0:1], 12, v[0:1]
	s_or_b32 s4, s33, s4
	v_lshl_add_u64 v[128:129], v[158:159], 0, v[0:1]
	v_add_u32_e32 v0, s4, v187
	v_ashrrev_i32_e32 v1, 31, v0
	v_lshlrev_b64 v[0:1], 12, v[0:1]
	v_lshl_add_u64 v[130:131], v[160:161], 0, v[0:1]
	s_mov_b64 s[4:5], 0
	s_mov_b32 s43, 0
	v_mov_b32_e32 v0, 0
	v_mov_b32_e32 v1, v145
	v_mov_b32_e32 v2, v145
	v_mov_b32_e32 v3, v145
	v_mov_b32_e32 v4, v145
	v_mov_b32_e32 v5, v145
	v_mov_b32_e32 v6, v145
	v_mov_b32_e32 v7, v145
	s_waitcnt vmcnt(0)
	v_mov_b32_e32 v8, v145
	v_mov_b32_e32 v9, v145
	v_mov_b32_e32 v10, v145
	v_mov_b32_e32 v11, v145
	v_mov_b32_e32 v12, v145
	v_mov_b32_e32 v13, v145
	v_mov_b32_e32 v14, v145
	v_mov_b32_e32 v15, v145
	v_mov_b32_e32 v16, 0
	v_mov_b32_e32 v17, v145
	v_mov_b32_e32 v18, v145
	v_mov_b32_e32 v19, v145
	v_mov_b32_e32 v20, v145
	v_mov_b32_e32 v21, v145
	v_mov_b32_e32 v22, v145
	v_mov_b32_e32 v23, v145
	v_mov_b32_e32 v24, v145
	v_mov_b32_e32 v25, v145
	v_mov_b32_e32 v26, v145
	v_mov_b32_e32 v27, v145
	v_mov_b32_e32 v28, v145
	v_mov_b32_e32 v29, v145
	v_mov_b32_e32 v30, v145
	v_mov_b32_e32 v31, v145
	v_mov_b32_e32 v32, 0
	v_mov_b32_e32 v33, v145
	v_mov_b32_e32 v34, v145
	v_mov_b32_e32 v35, v145
	v_mov_b32_e32 v36, v145
	v_mov_b32_e32 v37, v145
	v_mov_b32_e32 v38, v145
	v_mov_b32_e32 v39, v145
	v_mov_b32_e32 v40, v145
	v_mov_b32_e32 v41, v145
	v_mov_b32_e32 v42, v145
	v_mov_b32_e32 v43, v145
	v_mov_b32_e32 v44, v145
	v_mov_b32_e32 v45, v145
	v_mov_b32_e32 v46, v145
	v_mov_b32_e32 v47, v145
	v_mov_b32_e32 v48, 0
	v_mov_b32_e32 v49, v145
	v_mov_b32_e32 v50, v145
	v_mov_b32_e32 v51, v145
	v_mov_b32_e32 v52, v145
	v_mov_b32_e32 v53, v145
	v_mov_b32_e32 v54, v145
	v_mov_b32_e32 v55, v145
	v_mov_b32_e32 v56, v145
	v_mov_b32_e32 v57, v145
	v_mov_b32_e32 v58, v145
	v_mov_b32_e32 v59, v145
	v_mov_b32_e32 v60, v145
	v_mov_b32_e32 v61, v145
	v_mov_b32_e32 v62, v145
	v_mov_b32_e32 v63, v145
	v_mov_b32_e32 v64, 0
	v_mov_b32_e32 v65, v145
	v_mov_b32_e32 v66, v145
	v_mov_b32_e32 v67, v145
	v_mov_b32_e32 v68, v145
	v_mov_b32_e32 v69, v145
	v_mov_b32_e32 v70, v145
	v_mov_b32_e32 v71, v145
	v_mov_b32_e32 v72, v145
	v_mov_b32_e32 v73, v145
	v_mov_b32_e32 v74, v145
	v_mov_b32_e32 v75, v145
	v_mov_b32_e32 v76, v145
	v_mov_b32_e32 v77, v145
	v_mov_b32_e32 v78, v145
	v_mov_b32_e32 v79, v145
	v_mov_b32_e32 v80, 0
	v_mov_b32_e32 v81, v145
	v_mov_b32_e32 v82, v145
	v_mov_b32_e32 v83, v145
	v_mov_b32_e32 v84, v145
	v_mov_b32_e32 v85, v145
	v_mov_b32_e32 v86, v145
	v_mov_b32_e32 v87, v145
	v_mov_b32_e32 v88, v145
	v_mov_b32_e32 v89, v145
	v_mov_b32_e32 v90, v145
	v_mov_b32_e32 v91, v145
	v_mov_b32_e32 v92, v145
	v_mov_b32_e32 v93, v145
	v_mov_b32_e32 v94, v145
	v_mov_b32_e32 v95, v145
	v_mov_b32_e32 v96, 0
	v_mov_b32_e32 v97, v145
	v_mov_b32_e32 v98, v145
	v_mov_b32_e32 v99, v145
	v_mov_b32_e32 v100, v145
	v_mov_b32_e32 v101, v145
	v_mov_b32_e32 v102, v145
	v_mov_b32_e32 v103, v145
	v_mov_b32_e32 v104, v145
	v_mov_b32_e32 v105, v145
	v_mov_b32_e32 v106, v145
	v_mov_b32_e32 v107, v145
	v_mov_b32_e32 v108, v145
	v_mov_b32_e32 v109, v145
	v_mov_b32_e32 v110, v145
	v_mov_b32_e32 v111, v145
	v_mov_b32_e32 v112, 0
	v_mov_b32_e32 v113, v145
	v_mov_b32_e32 v114, v145
	v_mov_b32_e32 v115, v145
	v_mov_b32_e32 v116, v145
	v_mov_b32_e32 v117, v145
	v_mov_b32_e32 v118, v145
	v_mov_b32_e32 v119, v145
	v_mov_b32_e32 v120, v145
	v_mov_b32_e32 v121, v145
	v_mov_b32_e32 v122, v145
	v_mov_b32_e32 v123, v145
	v_mov_b32_e32 v124, v145
	v_mov_b32_e32 v125, v145
	v_mov_b32_e32 v126, v145
	v_mov_b32_e32 v127, v145
	s_waitcnt lgkmcnt(0)
	s_barrier
	v_readfirstlane_b32 s48, v188
	s_sub_u32 s48, s48, 16
	s_mov_b32 s49, 0
	s_mov_b32 s50, 0x8000
	s_mov_b32 s52, 0x10000
	v_and_b32_e32 v140, 63, v186
	v_and_b32_e32 v141, 15, v140
	v_lshrrev_b32_e32 v136, 4, v140
	v_bfe_u32 v137, v140, 1, 3
	v_xor_b32_e32 v132, v136, v137
	v_or_b32_e32 v136, 4, v136
	v_xor_b32_e32 v133, v136, v137
	v_lshlrev_b32_e32 v132, 4, v132
	v_lshlrev_b32_e32 v133, 4, v133
	v_lshl_add_u32 v132, v141, 7, v132
	v_lshl_add_u32 v133, v141, 7, v133
	v_bfe_u32 v136, v186, 6, 2
	v_lshl_add_u32 v134, v136, 13, v132
	v_lshl_add_u32 v135, v136, 13, v133
	v_lshrrev_b32_e32 v136, 8, v186
	v_lshl_add_u32 v132, v136, 14, v132
	v_lshl_add_u32 v133, v136, 14, v133
	v_readfirstlane_b32 s56, v128
	v_readfirstlane_b32 s57, v129
	s_and_b32 s53, s48, 0x400
	s_lshr_b32 s53, s53, 4
	s_sub_u32 s56, s56, s53
	s_subb_u32 s57, s57, 0
	v_subrev_u32_e32 v138, s56, v128
	s_add_u32 s62, s56, s28
	s_addc_u32 s63, s57, s29
	s_add_u32 s60, s56, s26
	s_addc_u32 s61, s57, s27
	s_add_u32 s58, s56, s24
	s_addc_u32 s59, s57, s25
	s_add_u32 s56, s56, s22
	s_addc_u32 s57, s57, s23
	v_readfirstlane_b32 s64, v130
	v_readfirstlane_b32 s65, v131
	s_and_b32 s53, s48, 0x400
	s_lshr_b32 s53, s53, 4
	s_sub_u32 s64, s64, s53
	s_subb_u32 s65, s65, 0
	v_subrev_u32_e32 v139, s64, v130
	s_add_u32 s70, s64, s28
	s_addc_u32 s71, s65, s29
	s_add_u32 s68, s64, s26
	s_addc_u32 s69, s65, s27
	s_add_u32 s66, s64, s24
	s_addc_u32 s67, s65, s25
	s_add_u32 s64, s64, s22
	s_addc_u32 s65, s65, s23
	s_add_u32 m0, s52, s48
	s_nop 0
	global_load_lds_dwordx4 v138, s[56:57]
	s_add_u32 s56, s56, 0x80
	s_addc_u32 s57, s57, 0
	s_add_u32 s53, s52, s48
	s_add_u32 m0, s53, 0x2000
	s_nop 0
	global_load_lds_dwordx4 v138, s[58:59]
	s_add_u32 s58, s58, 0x80
	s_addc_u32 s59, s59, 0
	s_add_u32 s53, s52, s48
	s_add_u32 m0, s53, 0x4000
	s_nop 0
	global_load_lds_dwordx4 v138, s[60:61]
	s_add_u32 s60, s60, 0x80
	s_addc_u32 s61, s61, 0
	s_add_u32 s53, s52, s48
	s_add_u32 m0, s53, 0x6000
	s_nop 0
	global_load_lds_dwordx4 v138, s[62:63]
	s_add_u32 s62, s62, 0x80
	s_addc_u32 s63, s63, 0
	v_add_u32_e32 v137, s50, v134
	v_add_u32_e32 v136, s49, v132
	ds_read_b128 v[164:167], v137
	ds_read_b128 v[168:171], v137 offset:2048
	ds_read_b128 v[172:175], v137 offset:4096
	ds_read_b128 v[176:179], v137 offset:6144
	ds_read_b128 v[224:227], v136
	ds_read_b128 v[228:231], v136 offset:2048
	ds_read_b128 v[232:235], v136 offset:4096
	ds_read_b128 v[236:239], v136 offset:6144
.Lg161_loop:
	s_add_u32 s51, s50, 0x10000
	s_sub_u32 s53, s51, 0x28000
	s_cmp_ge_u32 s51, 0x28000
	s_cselect_b32 s51, s53, s51
	s_add_u32 s52, s49, 0x20000
	s_sub_u32 s53, s52, 0x28000
	s_cmp_ge_u32 s52, 0x28000
	s_cselect_b32 s52, s53, s52
	v_add_u32_e32 v137, s50, v135
	s_waitcnt lgkmcnt(4)
	s_waitcnt lgkmcnt(3)
	v_mfma_f32_16x16x32_bf16 v[112:115], v[164:167], v[224:227], v[112:115]
	v_mfma_f32_16x16x32_bf16 v[120:123], v[168:171], v[224:227], v[120:123]
	v_mfma_f32_16x16x32_bf16 v[96:99], v[172:175], v[224:227], v[96:99]
	v_mfma_f32_16x16x32_bf16 v[104:107], v[176:179], v[224:227], v[104:107]
	s_add_u32 m0, s51, s48
	s_nop 0
	global_load_lds_dwordx4 v139, s[64:65]
	s_add_u32 s64, s64, 0x80
	s_addc_u32 s65, s65, 0
	ds_read_b128 v[224:227], v136 offset:8192
	ds_read_b128 v[180:183], v137
	s_waitcnt lgkmcnt(4)
	v_mfma_f32_16x16x32_bf16 v[116:119], v[164:167], v[228:231], v[116:119]
	v_mfma_f32_16x16x32_bf16 v[124:127], v[168:171], v[228:231], v[124:127]
	v_mfma_f32_16x16x32_bf16 v[100:103], v[172:175], v[228:231], v[100:103]
	v_mfma_f32_16x16x32_bf16 v[108:111], v[176:179], v[228:231], v[108:111]
	s_add_u32 s53, s51, s48
	s_add_u32 m0, s53, 0x2000
	s_nop 0
	global_load_lds_dwordx4 v139, s[66:67]
	s_add_u32 s66, s66, 0x80
	s_addc_u32 s67, s67, 0
	ds_read_b128 v[228:231], v136 offset:10240
	ds_read_b128 v[212:215], v137 offset:2048
	s_waitcnt lgkmcnt(5)
	v_mfma_f32_16x16x32_bf16 v[80:83], v[164:167], v[232:235], v[80:83]
	v_mfma_f32_16x16x32_bf16 v[88:91], v[168:171], v[232:235], v[88:91]
	v_mfma_f32_16x16x32_bf16 v[64:67], v[172:175], v[232:235], v[64:67]
	v_mfma_f32_16x16x32_bf16 v[72:75], v[176:179], v[232:235], v[72:75]
	s_add_u32 s53, s51, s48
	s_add_u32 m0, s53, 0x4000
	s_nop 0
	global_load_lds_dwordx4 v139, s[68:69]
	s_add_u32 s68, s68, 0x80
	s_addc_u32 s69, s69, 0
	ds_read_b128 v[232:235], v136 offset:12288
	ds_read_b128 v[216:219], v137 offset:4096
	s_waitcnt lgkmcnt(6)
	v_mfma_f32_16x16x32_bf16 v[84:87], v[164:167], v[236:239], v[84:87]
	v_mfma_f32_16x16x32_bf16 v[92:95], v[168:171], v[236:239], v[92:95]
	v_mfma_f32_16x16x32_bf16 v[68:71], v[172:175], v[236:239], v[68:71]
	v_mfma_f32_16x16x32_bf16 v[76:79], v[176:179], v[236:239], v[76:79]
	s_add_u32 s53, s51, s48
	s_add_u32 m0, s53, 0x6000
	s_nop 0
	global_load_lds_dwordx4 v139, s[70:71]
	s_add_u32 s70, s70, 0x80
	s_addc_u32 s71, s71, 0
	ds_read_b128 v[236:239], v136 offset:14336
	ds_read_b128 v[220:223], v137 offset:6144
	v_add_u32_e32 v136, s49, v133
	s_waitcnt lgkmcnt(7)
	v_mfma_f32_16x16x32_bf16 v[48:51], v[164:167], v[224:227], v[48:51]
	v_mfma_f32_16x16x32_bf16 v[56:59], v[168:171], v[224:227], v[56:59]
	v_mfma_f32_16x16x32_bf16 v[32:35], v[172:175], v[224:227], v[32:35]
	v_mfma_f32_16x16x32_bf16 v[40:43], v[176:179], v[224:227], v[40:43]
	s_add_u32 m0, s52, s48
	s_nop 0
	global_load_lds_dwordx4 v138, s[56:57]
	s_add_u32 s56, s56, 0x80
	s_addc_u32 s57, s57, 0
	ds_read_b128 v[224:227], v136
	s_waitcnt lgkmcnt(6)
	v_mfma_f32_16x16x32_bf16 v[52:55], v[164:167], v[228:231], v[52:55]
	v_mfma_f32_16x16x32_bf16 v[60:63], v[168:171], v[228:231], v[60:63]
	v_mfma_f32_16x16x32_bf16 v[36:39], v[172:175], v[228:231], v[36:39]
	v_mfma_f32_16x16x32_bf16 v[44:47], v[176:179], v[228:231], v[44:47]
	s_add_u32 s53, s52, s48
	s_add_u32 m0, s53, 0x2000
	s_nop 0
	global_load_lds_dwordx4 v138, s[58:59]
	s_add_u32 s58, s58, 0x80
	s_addc_u32 s59, s59, 0
	ds_read_b128 v[228:231], v136 offset:2048
	s_waitcnt lgkmcnt(5)
	v_mfma_f32_16x16x32_bf16 v[16:19], v[164:167], v[232:235], v[16:19]
	v_mfma_f32_16x16x32_bf16 v[24:27], v[168:171], v[232:235], v[24:27]
	v_mfma_f32_16x16x32_bf16 v[0:3], v[172:175], v[232:235], v[0:3]
	v_mfma_f32_16x16x32_bf16 v[8:11], v[176:179], v[232:235], v[8:11]
	s_add_u32 s53, s52, s48
	s_add_u32 m0, s53, 0x4000
	s_nop 0
	global_load_lds_dwordx4 v138, s[60:61]
	s_add_u32 s60, s60, 0x80
	s_addc_u32 s61, s61, 0
	ds_read_b128 v[232:235], v136 offset:4096
	s_waitcnt lgkmcnt(4)
	v_mfma_f32_16x16x32_bf16 v[20:23], v[164:167], v[236:239], v[20:23]
	v_mfma_f32_16x16x32_bf16 v[28:31], v[168:171], v[236:239], v[28:31]
	v_mfma_f32_16x16x32_bf16 v[4:7], v[172:175], v[236:239], v[4:7]
	v_mfma_f32_16x16x32_bf16 v[12:15], v[176:179], v[236:239], v[12:15]
	s_add_u32 s53, s52, s48
	s_add_u32 m0, s53, 0x6000
	s_nop 0
	global_load_lds_dwordx4 v138, s[62:63]
	s_add_u32 s62, s62, 0x80
	s_addc_u32 s63, s63, 0
	ds_read_b128 v[236:239], v136 offset:6144
	s_waitcnt lgkmcnt(4)
	s_waitcnt lgkmcnt(3)
	v_mfma_f32_16x16x32_bf16 v[112:115], v[180:183], v[224:227], v[112:115]
	v_mfma_f32_16x16x32_bf16 v[120:123], v[212:215], v[224:227], v[120:123]
	v_mfma_f32_16x16x32_bf16 v[96:99], v[216:219], v[224:227], v[96:99]
	v_mfma_f32_16x16x32_bf16 v[104:107], v[220:223], v[224:227], v[104:107]
	ds_read_b128 v[224:227], v136 offset:8192
	s_waitcnt lgkmcnt(3)
	v_mfma_f32_16x16x32_bf16 v[116:119], v[180:183], v[228:231], v[116:119]
	v_mfma_f32_16x16x32_bf16 v[124:127], v[212:215], v[228:231], v[124:127]
	v_mfma_f32_16x16x32_bf16 v[100:103], v[216:219], v[228:231], v[100:103]
	v_mfma_f32_16x16x32_bf16 v[108:111], v[220:223], v[228:231], v[108:111]
	ds_read_b128 v[228:231], v136 offset:10240
	s_waitcnt lgkmcnt(3)
	v_mfma_f32_16x16x32_bf16 v[80:83], v[180:183], v[232:235], v[80:83]
	v_mfma_f32_16x16x32_bf16 v[88:91], v[212:215], v[232:235], v[88:91]
	v_mfma_f32_16x16x32_bf16 v[64:67], v[216:219], v[232:235], v[64:67]
	v_mfma_f32_16x16x32_bf16 v[72:75], v[220:223], v[232:235], v[72:75]
	ds_read_b128 v[232:235], v136 offset:12288
	s_waitcnt lgkmcnt(3)
	v_mfma_f32_16x16x32_bf16 v[84:87], v[180:183], v[236:239], v[84:87]
	v_mfma_f32_16x16x32_bf16 v[92:95], v[212:215], v[236:239], v[92:95]
	v_mfma_f32_16x16x32_bf16 v[68:71], v[216:219], v[236:239], v[68:71]
	v_mfma_f32_16x16x32_bf16 v[76:79], v[220:223], v[236:239], v[76:79]
	ds_read_b128 v[236:239], v136 offset:14336
	s_waitcnt lgkmcnt(3)
	v_mfma_f32_16x16x32_bf16 v[48:51], v[180:183], v[224:227], v[48:51]
	v_mfma_f32_16x16x32_bf16 v[56:59], v[212:215], v[224:227], v[56:59]
	v_mfma_f32_16x16x32_bf16 v[32:35], v[216:219], v[224:227], v[32:35]
	v_mfma_f32_16x16x32_bf16 v[40:43], v[220:223], v[224:227], v[40:43]
	s_waitcnt lgkmcnt(2)
	v_mfma_f32_16x16x32_bf16 v[52:55], v[180:183], v[228:231], v[52:55]
	v_mfma_f32_16x16x32_bf16 v[60:63], v[212:215], v[228:231], v[60:63]
	v_mfma_f32_16x16x32_bf16 v[36:39], v[216:219], v[228:231], v[36:39]
	v_mfma_f32_16x16x32_bf16 v[44:47], v[220:223], v[228:231], v[44:47]
	s_waitcnt lgkmcnt(0)
	s_add_u32 s4, s4, 0x80
	s_addc_u32 s5, s5, 0
	s_add_u32 s49, s49, 0x10000
	s_sub_u32 s53, s49, 0x28000
	s_cmp_ge_u32 s49, 0x28000
	s_cselect_b32 s49, s53, s49
	s_mov_b32 s50, s51
	s_waitcnt vmcnt(4)
	s_barrier
	v_add_u32_e32 v137, s50, v134
	v_add_u32_e32 v136, s49, v132
	ds_read_b128 v[164:167], v137
	ds_read_b128 v[168:171], v137 offset:2048
	ds_read_b128 v[172:175], v137 offset:4096
	ds_read_b128 v[176:179], v137 offset:6144
	ds_read_b128 v[224:227], v136
	ds_read_b128 v[228:231], v136 offset:2048
	v_mfma_f32_16x16x32_bf16 v[16:19], v[180:183], v[232:235], v[16:19]
	v_mfma_f32_16x16x32_bf16 v[24:27], v[212:215], v[232:235], v[24:27]
	v_mfma_f32_16x16x32_bf16 v[0:3], v[216:219], v[232:235], v[0:3]
	v_mfma_f32_16x16x32_bf16 v[8:11], v[220:223], v[232:235], v[8:11]
	ds_read_b128 v[232:235], v136 offset:4096
	v_mfma_f32_16x16x32_bf16 v[20:23], v[180:183], v[236:239], v[20:23]
	v_mfma_f32_16x16x32_bf16 v[28:31], v[212:215], v[236:239], v[28:31]
	v_mfma_f32_16x16x32_bf16 v[4:7], v[216:219], v[236:239], v[4:7]
	v_mfma_f32_16x16x32_bf16 v[12:15], v[220:223], v[236:239], v[12:15]
	ds_read_b128 v[236:239], v136 offset:6144
	s_cmpk_lg_i32 s4, 0xf00
	s_cbranch_scc1 .Lg161_loop
	s_add_u32 s51, s50, 0x10000
	s_sub_u32 s53, s51, 0x28000
	s_cmp_ge_u32 s51, 0x28000
	s_cselect_b32 s51, s53, s51
	v_add_u32_e32 v137, s50, v135
	s_waitcnt lgkmcnt(4)
	s_waitcnt lgkmcnt(3)
	v_mfma_f32_16x16x32_bf16 v[112:115], v[164:167], v[224:227], v[112:115]
	v_mfma_f32_16x16x32_bf16 v[120:123], v[168:171], v[224:227], v[120:123]
	v_mfma_f32_16x16x32_bf16 v[96:99], v[172:175], v[224:227], v[96:99]
	v_mfma_f32_16x16x32_bf16 v[104:107], v[176:179], v[224:227], v[104:107]
	s_add_u32 m0, s51, s48
	s_nop 0
	global_load_lds_dwordx4 v139, s[64:65]
	s_add_u32 s64, s64, 0x80
	s_addc_u32 s65, s65, 0
	ds_read_b128 v[224:227], v136 offset:8192
	ds_read_b128 v[180:183], v137
	s_waitcnt lgkmcnt(4)
	v_mfma_f32_16x16x32_bf16 v[116:119], v[164:167], v[228:231], v[116:119]
	v_mfma_f32_16x16x32_bf16 v[124:127], v[168:171], v[228:231], v[124:127]
	v_mfma_f32_16x16x32_bf16 v[100:103], v[172:175], v[228:231], v[100:103]
	v_mfma_f32_16x16x32_bf16 v[108:111], v[176:179], v[228:231], v[108:111]
	s_add_u32 s53, s51, s48
	s_add_u32 m0, s53, 0x2000
	s_nop 0
	global_load_lds_dwordx4 v139, s[66:67]
	s_add_u32 s66, s66, 0x80
	s_addc_u32 s67, s67, 0
	ds_read_b128 v[228:231], v136 offset:10240
	ds_read_b128 v[212:215], v137 offset:2048
	s_waitcnt lgkmcnt(5)
	v_mfma_f32_16x16x32_bf16 v[80:83], v[164:167], v[232:235], v[80:83]
	v_mfma_f32_16x16x32_bf16 v[88:91], v[168:171], v[232:235], v[88:91]
	v_mfma_f32_16x16x32_bf16 v[64:67], v[172:175], v[232:235], v[64:67]
	v_mfma_f32_16x16x32_bf16 v[72:75], v[176:179], v[232:235], v[72:75]
	s_add_u32 s53, s51, s48
	s_add_u32 m0, s53, 0x4000
	s_nop 0
	global_load_lds_dwordx4 v139, s[68:69]
	s_add_u32 s68, s68, 0x80
	s_addc_u32 s69, s69, 0
	ds_read_b128 v[232:235], v136 offset:12288
	ds_read_b128 v[216:219], v137 offset:4096
	s_waitcnt lgkmcnt(6)
	v_mfma_f32_16x16x32_bf16 v[84:87], v[164:167], v[236:239], v[84:87]
	v_mfma_f32_16x16x32_bf16 v[92:95], v[168:171], v[236:239], v[92:95]
	v_mfma_f32_16x16x32_bf16 v[68:71], v[172:175], v[236:239], v[68:71]
	v_mfma_f32_16x16x32_bf16 v[76:79], v[176:179], v[236:239], v[76:79]
	s_add_u32 s53, s51, s48
	s_add_u32 m0, s53, 0x6000
	s_nop 0
	global_load_lds_dwordx4 v139, s[70:71]
	s_add_u32 s70, s70, 0x80
	s_addc_u32 s71, s71, 0
	ds_read_b128 v[236:239], v136 offset:14336
	ds_read_b128 v[220:223], v137 offset:6144
	v_add_u32_e32 v136, s49, v133
	s_waitcnt lgkmcnt(7)
	v_mfma_f32_16x16x32_bf16 v[48:51], v[164:167], v[224:227], v[48:51]
	v_mfma_f32_16x16x32_bf16 v[56:59], v[168:171], v[224:227], v[56:59]
	v_mfma_f32_16x16x32_bf16 v[32:35], v[172:175], v[224:227], v[32:35]
	v_mfma_f32_16x16x32_bf16 v[40:43], v[176:179], v[224:227], v[40:43]
	ds_read_b128 v[224:227], v136
	s_waitcnt lgkmcnt(6)
	v_mfma_f32_16x16x32_bf16 v[52:55], v[164:167], v[228:231], v[52:55]
	v_mfma_f32_16x16x32_bf16 v[60:63], v[168:171], v[228:231], v[60:63]
	v_mfma_f32_16x16x32_bf16 v[36:39], v[172:175], v[228:231], v[36:39]
	v_mfma_f32_16x16x32_bf16 v[44:47], v[176:179], v[228:231], v[44:47]
	ds_read_b128 v[228:231], v136 offset:2048
	s_waitcnt lgkmcnt(5)
	v_mfma_f32_16x16x32_bf16 v[16:19], v[164:167], v[232:235], v[16:19]
	v_mfma_f32_16x16x32_bf16 v[24:27], v[168:171], v[232:235], v[24:27]
	v_mfma_f32_16x16x32_bf16 v[0:3], v[172:175], v[232:235], v[0:3]
	v_mfma_f32_16x16x32_bf16 v[8:11], v[176:179], v[232:235], v[8:11]
	ds_read_b128 v[232:235], v136 offset:4096
	s_waitcnt lgkmcnt(4)
	v_mfma_f32_16x16x32_bf16 v[20:23], v[164:167], v[236:239], v[20:23]
	v_mfma_f32_16x16x32_bf16 v[28:31], v[168:171], v[236:239], v[28:31]
	v_mfma_f32_16x16x32_bf16 v[4:7], v[172:175], v[236:239], v[4:7]
	v_mfma_f32_16x16x32_bf16 v[12:15], v[176:179], v[236:239], v[12:15]
	ds_read_b128 v[236:239], v136 offset:6144
	s_waitcnt lgkmcnt(4)
	s_waitcnt lgkmcnt(3)
	v_mfma_f32_16x16x32_bf16 v[112:115], v[180:183], v[224:227], v[112:115]
	v_mfma_f32_16x16x32_bf16 v[120:123], v[212:215], v[224:227], v[120:123]
	v_mfma_f32_16x16x32_bf16 v[96:99], v[216:219], v[224:227], v[96:99]
	v_mfma_f32_16x16x32_bf16 v[104:107], v[220:223], v[224:227], v[104:107]
	ds_read_b128 v[224:227], v136 offset:8192
	s_waitcnt lgkmcnt(3)
	v_mfma_f32_16x16x32_bf16 v[116:119], v[180:183], v[228:231], v[116:119]
	v_mfma_f32_16x16x32_bf16 v[124:127], v[212:215], v[228:231], v[124:127]
	v_mfma_f32_16x16x32_bf16 v[100:103], v[216:219], v[228:231], v[100:103]
	v_mfma_f32_16x16x32_bf16 v[108:111], v[220:223], v[228:231], v[108:111]
	ds_read_b128 v[228:231], v136 offset:10240
	s_waitcnt lgkmcnt(3)
	v_mfma_f32_16x16x32_bf16 v[80:83], v[180:183], v[232:235], v[80:83]
	v_mfma_f32_16x16x32_bf16 v[88:91], v[212:215], v[232:235], v[88:91]
	v_mfma_f32_16x16x32_bf16 v[64:67], v[216:219], v[232:235], v[64:67]
	v_mfma_f32_16x16x32_bf16 v[72:75], v[220:223], v[232:235], v[72:75]
	ds_read_b128 v[232:235], v136 offset:12288
	s_waitcnt lgkmcnt(3)
	v_mfma_f32_16x16x32_bf16 v[84:87], v[180:183], v[236:239], v[84:87]
	v_mfma_f32_16x16x32_bf16 v[92:95], v[212:215], v[236:239], v[92:95]
	v_mfma_f32_16x16x32_bf16 v[68:71], v[216:219], v[236:239], v[68:71]
	v_mfma_f32_16x16x32_bf16 v[76:79], v[220:223], v[236:239], v[76:79]
	ds_read_b128 v[236:239], v136 offset:14336
	s_waitcnt lgkmcnt(3)
	v_mfma_f32_16x16x32_bf16 v[48:51], v[180:183], v[224:227], v[48:51]
	v_mfma_f32_16x16x32_bf16 v[56:59], v[212:215], v[224:227], v[56:59]
	v_mfma_f32_16x16x32_bf16 v[32:35], v[216:219], v[224:227], v[32:35]
	v_mfma_f32_16x16x32_bf16 v[40:43], v[220:223], v[224:227], v[40:43]
	s_waitcnt lgkmcnt(2)
	v_mfma_f32_16x16x32_bf16 v[52:55], v[180:183], v[228:231], v[52:55]
	v_mfma_f32_16x16x32_bf16 v[60:63], v[212:215], v[228:231], v[60:63]
	v_mfma_f32_16x16x32_bf16 v[36:39], v[216:219], v[228:231], v[36:39]
	v_mfma_f32_16x16x32_bf16 v[44:47], v[220:223], v[228:231], v[44:47]
	s_waitcnt lgkmcnt(0)
	s_add_u32 s4, s4, 0x80
	s_addc_u32 s5, s5, 0
	s_add_u32 s49, s49, 0x10000
	s_sub_u32 s53, s49, 0x28000
	s_cmp_ge_u32 s49, 0x28000
	s_cselect_b32 s49, s53, s49
	s_mov_b32 s50, s51
	s_waitcnt vmcnt(0)
	s_barrier
	v_add_u32_e32 v137, s50, v134
	v_add_u32_e32 v136, s49, v132
	ds_read_b128 v[164:167], v137
	ds_read_b128 v[168:171], v137 offset:2048
	ds_read_b128 v[172:175], v137 offset:4096
	ds_read_b128 v[176:179], v137 offset:6144
	ds_read_b128 v[224:227], v136
	ds_read_b128 v[228:231], v136 offset:2048
	v_mfma_f32_16x16x32_bf16 v[16:19], v[180:183], v[232:235], v[16:19]
	v_mfma_f32_16x16x32_bf16 v[24:27], v[212:215], v[232:235], v[24:27]
	v_mfma_f32_16x16x32_bf16 v[0:3], v[216:219], v[232:235], v[0:3]
	v_mfma_f32_16x16x32_bf16 v[8:11], v[220:223], v[232:235], v[8:11]
	ds_read_b128 v[232:235], v136 offset:4096
	v_mfma_f32_16x16x32_bf16 v[20:23], v[180:183], v[236:239], v[20:23]
	v_mfma_f32_16x16x32_bf16 v[28:31], v[212:215], v[236:239], v[28:31]
	v_mfma_f32_16x16x32_bf16 v[4:7], v[216:219], v[236:239], v[4:7]
	v_mfma_f32_16x16x32_bf16 v[12:15], v[220:223], v[236:239], v[12:15]
	ds_read_b128 v[236:239], v136 offset:6144
	v_add_u32_e32 v137, s50, v135
	s_waitcnt lgkmcnt(4)
	s_waitcnt lgkmcnt(3)
	v_mfma_f32_16x16x32_bf16 v[112:115], v[164:167], v[224:227], v[112:115]
	v_mfma_f32_16x16x32_bf16 v[120:123], v[168:171], v[224:227], v[120:123]
	v_mfma_f32_16x16x32_bf16 v[96:99], v[172:175], v[224:227], v[96:99]
	v_mfma_f32_16x16x32_bf16 v[104:107], v[176:179], v[224:227], v[104:107]
	ds_read_b128 v[224:227], v136 offset:8192
	ds_read_b128 v[180:183], v137
	s_waitcnt lgkmcnt(4)
	v_mfma_f32_16x16x32_bf16 v[116:119], v[164:167], v[228:231], v[116:119]
	v_mfma_f32_16x16x32_bf16 v[124:127], v[168:171], v[228:231], v[124:127]
	v_mfma_f32_16x16x32_bf16 v[100:103], v[172:175], v[228:231], v[100:103]
	v_mfma_f32_16x16x32_bf16 v[108:111], v[176:179], v[228:231], v[108:111]
	ds_read_b128 v[228:231], v136 offset:10240
	ds_read_b128 v[212:215], v137 offset:2048
	s_waitcnt lgkmcnt(5)
	v_mfma_f32_16x16x32_bf16 v[80:83], v[164:167], v[232:235], v[80:83]
	v_mfma_f32_16x16x32_bf16 v[88:91], v[168:171], v[232:235], v[88:91]
	v_mfma_f32_16x16x32_bf16 v[64:67], v[172:175], v[232:235], v[64:67]
	v_mfma_f32_16x16x32_bf16 v[72:75], v[176:179], v[232:235], v[72:75]
	ds_read_b128 v[232:235], v136 offset:12288
	ds_read_b128 v[216:219], v137 offset:4096
	s_waitcnt lgkmcnt(6)
	v_mfma_f32_16x16x32_bf16 v[84:87], v[164:167], v[236:239], v[84:87]
	v_mfma_f32_16x16x32_bf16 v[92:95], v[168:171], v[236:239], v[92:95]
	v_mfma_f32_16x16x32_bf16 v[68:71], v[172:175], v[236:239], v[68:71]
	v_mfma_f32_16x16x32_bf16 v[76:79], v[176:179], v[236:239], v[76:79]
	ds_read_b128 v[236:239], v136 offset:14336
	ds_read_b128 v[220:223], v137 offset:6144
	v_add_u32_e32 v136, s49, v133
	s_waitcnt lgkmcnt(7)
	v_mfma_f32_16x16x32_bf16 v[48:51], v[164:167], v[224:227], v[48:51]
	v_mfma_f32_16x16x32_bf16 v[56:59], v[168:171], v[224:227], v[56:59]
	v_mfma_f32_16x16x32_bf16 v[32:35], v[172:175], v[224:227], v[32:35]
	v_mfma_f32_16x16x32_bf16 v[40:43], v[176:179], v[224:227], v[40:43]
	ds_read_b128 v[224:227], v136
	s_waitcnt lgkmcnt(6)
	v_mfma_f32_16x16x32_bf16 v[52:55], v[164:167], v[228:231], v[52:55]
	v_mfma_f32_16x16x32_bf16 v[60:63], v[168:171], v[228:231], v[60:63]
	v_mfma_f32_16x16x32_bf16 v[36:39], v[172:175], v[228:231], v[36:39]
	v_mfma_f32_16x16x32_bf16 v[44:47], v[176:179], v[228:231], v[44:47]
	ds_read_b128 v[228:231], v136 offset:2048
	s_waitcnt lgkmcnt(5)
	v_mfma_f32_16x16x32_bf16 v[16:19], v[164:167], v[232:235], v[16:19]
	v_mfma_f32_16x16x32_bf16 v[24:27], v[168:171], v[232:235], v[24:27]
	v_mfma_f32_16x16x32_bf16 v[0:3], v[172:175], v[232:235], v[0:3]
	v_mfma_f32_16x16x32_bf16 v[8:11], v[176:179], v[232:235], v[8:11]
	ds_read_b128 v[232:235], v136 offset:4096
	s_waitcnt lgkmcnt(4)
	v_mfma_f32_16x16x32_bf16 v[20:23], v[164:167], v[236:239], v[20:23]
	v_mfma_f32_16x16x32_bf16 v[28:31], v[168:171], v[236:239], v[28:31]
	v_mfma_f32_16x16x32_bf16 v[4:7], v[172:175], v[236:239], v[4:7]
	v_mfma_f32_16x16x32_bf16 v[12:15], v[176:179], v[236:239], v[12:15]
	ds_read_b128 v[236:239], v136 offset:6144
	s_waitcnt lgkmcnt(4)
	s_waitcnt lgkmcnt(3)
	v_mfma_f32_16x16x32_bf16 v[112:115], v[180:183], v[224:227], v[112:115]
	v_mfma_f32_16x16x32_bf16 v[120:123], v[212:215], v[224:227], v[120:123]
	v_mfma_f32_16x16x32_bf16 v[96:99], v[216:219], v[224:227], v[96:99]
	v_mfma_f32_16x16x32_bf16 v[104:107], v[220:223], v[224:227], v[104:107]
	ds_read_b128 v[224:227], v136 offset:8192
	s_waitcnt lgkmcnt(3)
	v_mfma_f32_16x16x32_bf16 v[116:119], v[180:183], v[228:231], v[116:119]
	v_mfma_f32_16x16x32_bf16 v[124:127], v[212:215], v[228:231], v[124:127]
	v_mfma_f32_16x16x32_bf16 v[100:103], v[216:219], v[228:231], v[100:103]
	v_mfma_f32_16x16x32_bf16 v[108:111], v[220:223], v[228:231], v[108:111]
	ds_read_b128 v[228:231], v136 offset:10240
	s_waitcnt lgkmcnt(3)
	v_mfma_f32_16x16x32_bf16 v[80:83], v[180:183], v[232:235], v[80:83]
	v_mfma_f32_16x16x32_bf16 v[88:91], v[212:215], v[232:235], v[88:91]
	v_mfma_f32_16x16x32_bf16 v[64:67], v[216:219], v[232:235], v[64:67]
	v_mfma_f32_16x16x32_bf16 v[72:75], v[220:223], v[232:235], v[72:75]
	ds_read_b128 v[232:235], v136 offset:12288
	s_waitcnt lgkmcnt(3)
	v_mfma_f32_16x16x32_bf16 v[84:87], v[180:183], v[236:239], v[84:87]
	v_mfma_f32_16x16x32_bf16 v[92:95], v[212:215], v[236:239], v[92:95]
	v_mfma_f32_16x16x32_bf16 v[68:71], v[216:219], v[236:239], v[68:71]
	v_mfma_f32_16x16x32_bf16 v[76:79], v[220:223], v[236:239], v[76:79]
	ds_read_b128 v[236:239], v136 offset:14336
	s_waitcnt lgkmcnt(3)
	v_mfma_f32_16x16x32_bf16 v[48:51], v[180:183], v[224:227], v[48:51]
	v_mfma_f32_16x16x32_bf16 v[56:59], v[212:215], v[224:227], v[56:59]
	v_mfma_f32_16x16x32_bf16 v[32:35], v[216:219], v[224:227], v[32:35]
	v_mfma_f32_16x16x32_bf16 v[40:43], v[220:223], v[224:227], v[40:43]
	s_waitcnt lgkmcnt(2)
	v_mfma_f32_16x16x32_bf16 v[52:55], v[180:183], v[228:231], v[52:55]
	v_mfma_f32_16x16x32_bf16 v[60:63], v[212:215], v[228:231], v[60:63]
	v_mfma_f32_16x16x32_bf16 v[36:39], v[216:219], v[228:231], v[36:39]
	v_mfma_f32_16x16x32_bf16 v[44:47], v[220:223], v[228:231], v[44:47]
	s_waitcnt lgkmcnt(0)
	s_waitcnt vmcnt(0)
	s_barrier
	v_mfma_f32_16x16x32_bf16 v[16:19], v[180:183], v[232:235], v[16:19]
	v_mfma_f32_16x16x32_bf16 v[24:27], v[212:215], v[232:235], v[24:27]
	v_mfma_f32_16x16x32_bf16 v[0:3], v[216:219], v[232:235], v[0:3]
	v_mfma_f32_16x16x32_bf16 v[8:11], v[220:223], v[232:235], v[8:11]
	v_mfma_f32_16x16x32_bf16 v[20:23], v[180:183], v[236:239], v[20:23]
	v_mfma_f32_16x16x32_bf16 v[28:31], v[212:215], v[236:239], v[28:31]
	v_mfma_f32_16x16x32_bf16 v[4:7], v[216:219], v[236:239], v[4:7]
	v_mfma_f32_16x16x32_bf16 v[12:15], v[220:223], v[236:239], v[12:15]
	s_nop 15
	v_permlane16_swap_b32_e32 v112, v116
	v_permlane16_swap_b32_e32 v113, v117
	v_permlane16_swap_b32_e32 v114, v118
	v_permlane16_swap_b32_e32 v115, v119
	v_permlane16_swap_b32_e32 v120, v124
	v_permlane16_swap_b32_e32 v121, v125
	v_permlane16_swap_b32_e32 v122, v126
	v_permlane16_swap_b32_e32 v123, v127
	v_permlane16_swap_b32_e32 v96, v100
	v_permlane16_swap_b32_e32 v97, v101
	v_permlane16_swap_b32_e32 v98, v102
	v_permlane16_swap_b32_e32 v99, v103
	v_permlane16_swap_b32_e32 v104, v108
	v_permlane16_swap_b32_e32 v105, v109
	v_permlane16_swap_b32_e32 v106, v110
	v_permlane16_swap_b32_e32 v107, v111
	v_permlane16_swap_b32_e32 v80, v84
	v_permlane16_swap_b32_e32 v81, v85
	v_permlane16_swap_b32_e32 v82, v86
	v_permlane16_swap_b32_e32 v83, v87
	v_permlane16_swap_b32_e32 v88, v92
	v_permlane16_swap_b32_e32 v89, v93
	v_permlane16_swap_b32_e32 v90, v94
	v_permlane16_swap_b32_e32 v91, v95
	v_permlane16_swap_b32_e32 v64, v68
	v_permlane16_swap_b32_e32 v65, v69
	v_permlane16_swap_b32_e32 v66, v70
	v_permlane16_swap_b32_e32 v67, v71
	v_permlane16_swap_b32_e32 v72, v76
	v_permlane16_swap_b32_e32 v73, v77
	v_permlane16_swap_b32_e32 v74, v78
	v_permlane16_swap_b32_e32 v75, v79
	v_permlane16_swap_b32_e32 v48, v52
	v_permlane16_swap_b32_e32 v49, v53
	v_permlane16_swap_b32_e32 v50, v54
	v_permlane16_swap_b32_e32 v51, v55
	v_permlane16_swap_b32_e32 v56, v60
	v_permlane16_swap_b32_e32 v57, v61
	v_permlane16_swap_b32_e32 v58, v62
	v_permlane16_swap_b32_e32 v59, v63
	v_permlane16_swap_b32_e32 v32, v36
	v_permlane16_swap_b32_e32 v33, v37
	v_permlane16_swap_b32_e32 v34, v38
	v_permlane16_swap_b32_e32 v35, v39
	v_permlane16_swap_b32_e32 v40, v44
	v_permlane16_swap_b32_e32 v41, v45
	v_permlane16_swap_b32_e32 v42, v46
	v_permlane16_swap_b32_e32 v43, v47
	v_permlane16_swap_b32_e32 v16, v20
	v_permlane16_swap_b32_e32 v17, v21
	v_permlane16_swap_b32_e32 v18, v22
	v_permlane16_swap_b32_e32 v19, v23
	v_permlane16_swap_b32_e32 v24, v28
	v_permlane16_swap_b32_e32 v25, v29
	v_permlane16_swap_b32_e32 v26, v30
	v_permlane16_swap_b32_e32 v27, v31
	v_permlane16_swap_b32_e32 v0, v4
	v_permlane16_swap_b32_e32 v1, v5
	v_permlane16_swap_b32_e32 v2, v6
	v_permlane16_swap_b32_e32 v3, v7
	v_permlane16_swap_b32_e32 v8, v12
	v_permlane16_swap_b32_e32 v9, v13
	v_permlane16_swap_b32_e32 v10, v14
	v_permlane16_swap_b32_e32 v11, v15
	v_permlane32_swap_b32_e32 v112, v116
	v_permlane32_swap_b32_e32 v113, v117
	v_permlane32_swap_b32_e32 v114, v118
	v_permlane32_swap_b32_e32 v115, v119
	v_permlane32_swap_b32_e32 v120, v124
	v_permlane32_swap_b32_e32 v121, v125
	v_permlane32_swap_b32_e32 v122, v126
	v_permlane32_swap_b32_e32 v123, v127
	v_permlane32_swap_b32_e32 v96, v100
	v_permlane32_swap_b32_e32 v97, v101
	v_permlane32_swap_b32_e32 v98, v102
	v_permlane32_swap_b32_e32 v99, v103
	v_permlane32_swap_b32_e32 v104, v108
	v_permlane32_swap_b32_e32 v105, v109
	v_permlane32_swap_b32_e32 v106, v110
	v_permlane32_swap_b32_e32 v107, v111
	v_permlane32_swap_b32_e32 v80, v84
	v_permlane32_swap_b32_e32 v81, v85
	v_permlane32_swap_b32_e32 v82, v86
	v_permlane32_swap_b32_e32 v83, v87
	v_permlane32_swap_b32_e32 v88, v92
	v_permlane32_swap_b32_e32 v89, v93
	v_permlane32_swap_b32_e32 v90, v94
	v_permlane32_swap_b32_e32 v91, v95
	v_permlane32_swap_b32_e32 v64, v68
	v_permlane32_swap_b32_e32 v65, v69
	v_permlane32_swap_b32_e32 v66, v70
	v_permlane32_swap_b32_e32 v67, v71
	v_permlane32_swap_b32_e32 v72, v76
	v_permlane32_swap_b32_e32 v73, v77
	v_permlane32_swap_b32_e32 v74, v78
	v_permlane32_swap_b32_e32 v75, v79
	v_permlane32_swap_b32_e32 v48, v52
	v_permlane32_swap_b32_e32 v49, v53
	v_permlane32_swap_b32_e32 v50, v54
	v_permlane32_swap_b32_e32 v51, v55
	v_permlane32_swap_b32_e32 v56, v60
	v_permlane32_swap_b32_e32 v57, v61
	v_permlane32_swap_b32_e32 v58, v62
	v_permlane32_swap_b32_e32 v59, v63
	v_permlane32_swap_b32_e32 v32, v36
	v_permlane32_swap_b32_e32 v33, v37
	v_permlane32_swap_b32_e32 v34, v38
	v_permlane32_swap_b32_e32 v35, v39
	v_permlane32_swap_b32_e32 v40, v44
	v_permlane32_swap_b32_e32 v41, v45
	v_permlane32_swap_b32_e32 v42, v46
	v_permlane32_swap_b32_e32 v43, v47
	v_permlane32_swap_b32_e32 v16, v20
	v_permlane32_swap_b32_e32 v17, v21
	v_permlane32_swap_b32_e32 v18, v22
	v_permlane32_swap_b32_e32 v19, v23
	v_permlane32_swap_b32_e32 v24, v28
	v_permlane32_swap_b32_e32 v25, v29
	v_permlane32_swap_b32_e32 v26, v30
	v_permlane32_swap_b32_e32 v27, v31
	v_permlane32_swap_b32_e32 v0, v4
	v_permlane32_swap_b32_e32 v1, v5
	v_permlane32_swap_b32_e32 v2, v6
	v_permlane32_swap_b32_e32 v3, v7
	v_permlane32_swap_b32_e32 v8, v12
	v_permlane32_swap_b32_e32 v9, v13
	v_permlane32_swap_b32_e32 v10, v14
	v_permlane32_swap_b32_e32 v11, v15
	s_nop 1

.LBB0_164:
	s_ashr_i32 s33, s30, 2
	s_and_b32 s33, s33, -8
	s_or_b32 s33, s33, s3
	s_ashr_i32 s37, s33, 31
	s_lshr_b32 s37, s37, 29
	s_add_i32 s37, s33, s37
	s_ashr_i32 s39, s37, 3
	s_and_b32 s37, s37, 0x1ffff8
	s_sub_i32 s37, s33, s37
	s_lshl_b32 s38, s30, 8
	s_lshl_b32 s37, s37, 11
	s_and_b32 s38, s38, 0x700
	s_or_b32 s37, s37, s38
	s_lshl_b32 s38, s30, 5
	s_lshl_b32 s40, s39, 10
	s_and_b32 s38, s38, 0x300
	v_add_u32_e32 v0, s37, v149
	s_or_b32 s38, s40, s38
	v_ashrrev_i32_e32 v1, 31, v0
	v_add_u32_e32 v2, s38, v149
	v_lshlrev_b64 v[0:1], 12, v[0:1]
	v_ashrrev_i32_e32 v3, 31, v2
	v_readfirstlane_b32 s41, v150
	v_lshl_add_u64 v[0:1], v[130:131], 0, v[0:1]
	v_lshlrev_b64 v[2:3], 12, v[2:3]
	s_add_i32 m0, s41, -16
	v_readfirstlane_b32 s41, v128
	v_lshl_add_u64 v[2:3], v[132:133], 0, v[2:3]
	global_load_lds_dwordx4 v[0:1], off
	s_add_i32 m0, s41, -16
	v_readfirstlane_b32 s41, v160
	global_load_lds_dwordx4 v[2:3], off
	v_lshl_add_u64 v[4:5], v[0:1], 0, s[12:13]
	s_add_i32 m0, s41, -16
	v_readfirstlane_b32 s41, v161
	global_load_lds_dwordx4 v[4:5], off
	v_lshl_add_u64 v[4:5], v[2:3], 0, s[12:13]
	s_add_i32 m0, s41, -16
	v_readfirstlane_b32 s41, v162
	global_load_lds_dwordx4 v[4:5], off
	v_lshl_add_u64 v[4:5], v[0:1], 0, s[14:15]
	s_add_i32 m0, s41, -16
	v_readfirstlane_b32 s41, v163
	global_load_lds_dwordx4 v[4:5], off
	v_lshl_add_u64 v[4:5], v[2:3], 0, s[14:15]
	s_add_i32 m0, s41, -16
	v_readfirstlane_b32 s41, v164
	global_load_lds_dwordx4 v[4:5], off
	v_lshl_add_u64 v[0:1], v[0:1], 0, s[16:17]
	s_add_i32 m0, s41, -16
	v_readfirstlane_b32 s41, v165
	global_load_lds_dwordx4 v[0:1], off
	v_lshl_add_u64 v[0:1], v[2:3], 0, s[16:17]
	s_add_i32 m0, s41, -16
	s_and_b32 s28, s31, 0x700
	global_load_lds_dwordx4 v[0:1], off
	s_lshl_b32 s33, s33, 11
	s_or_b32 s28, s28, s33
	v_add_u32_e32 v0, s28, v149
	s_lshl_b32 s28, s39, 14
	v_subrev_u32_e32 v0, s28, v0
	s_and_b32 s29, s35, 0x300
	v_ashrrev_i32_e32 v1, 31, v0
	v_lshlrev_b64 v[0:1], 12, v[0:1]
	s_or_b32 s28, s29, s40
	v_lshl_add_u64 v[138:139], v[134:135], 0, v[0:1]
	v_add_u32_e32 v0, s28, v149
	v_ashrrev_i32_e32 v1, 31, v0
	v_lshlrev_b64 v[0:1], 12, v[0:1]
	v_lshl_add_u64 v[140:141], v[136:137], 0, v[0:1]
	s_mov_b32 s39, 0
	s_mov_b64 s[28:29], 0
	v_mov_b32_e32 v0, 0
	v_mov_b32_e32 v1, v129
	v_mov_b32_e32 v2, v129
	v_mov_b32_e32 v3, v129
	v_mov_b32_e32 v4, v129
	v_mov_b32_e32 v5, v129
	v_mov_b32_e32 v6, v129
	v_mov_b32_e32 v7, v129
	v_mov_b32_e32 v8, v129
	v_mov_b32_e32 v9, v129
	v_mov_b32_e32 v10, v129
	v_mov_b32_e32 v11, v129
	v_mov_b32_e32 v12, v129
	v_mov_b32_e32 v13, v129
	v_mov_b32_e32 v14, v129
	v_mov_b32_e32 v15, v129
	v_mov_b32_e32 v16, 0
	v_mov_b32_e32 v17, v129
	v_mov_b32_e32 v18, v129
	v_mov_b32_e32 v19, v129
	v_mov_b32_e32 v20, v129
	v_mov_b32_e32 v21, v129
	v_mov_b32_e32 v22, v129
	v_mov_b32_e32 v23, v129
	v_mov_b32_e32 v24, v129
	v_mov_b32_e32 v25, v129
	v_mov_b32_e32 v26, v129
	v_mov_b32_e32 v27, v129
	v_mov_b32_e32 v28, v129
	v_mov_b32_e32 v29, v129
	v_mov_b32_e32 v30, v129
	v_mov_b32_e32 v31, v129
	v_mov_b32_e32 v32, 0
	v_mov_b32_e32 v33, v129
	v_mov_b32_e32 v34, v129
	v_mov_b32_e32 v35, v129
	v_mov_b32_e32 v36, v129
	v_mov_b32_e32 v37, v129
	v_mov_b32_e32 v38, v129
	v_mov_b32_e32 v39, v129
	v_mov_b32_e32 v40, v129
	v_mov_b32_e32 v41, v129
	v_mov_b32_e32 v42, v129
	v_mov_b32_e32 v43, v129
	v_mov_b32_e32 v44, v129
	v_mov_b32_e32 v45, v129
	v_mov_b32_e32 v46, v129
	v_mov_b32_e32 v47, v129
	v_mov_b32_e32 v48, 0
	v_mov_b32_e32 v49, v129
	v_mov_b32_e32 v50, v129
	v_mov_b32_e32 v51, v129
	v_mov_b32_e32 v52, v129
	v_mov_b32_e32 v53, v129
	v_mov_b32_e32 v54, v129
	v_mov_b32_e32 v55, v129
	v_mov_b32_e32 v56, v129
	v_mov_b32_e32 v57, v129
	v_mov_b32_e32 v58, v129
	v_mov_b32_e32 v59, v129
	v_mov_b32_e32 v60, v129
	v_mov_b32_e32 v61, v129
	v_mov_b32_e32 v62, v129
	v_mov_b32_e32 v63, v129
	v_mov_b32_e32 v64, 0
	v_mov_b32_e32 v65, v129
	v_mov_b32_e32 v66, v129
	v_mov_b32_e32 v67, v129
	v_mov_b32_e32 v68, v129
	v_mov_b32_e32 v69, v129
	v_mov_b32_e32 v70, v129
	v_mov_b32_e32 v71, v129
	v_mov_b32_e32 v72, v129
	v_mov_b32_e32 v73, v129
	v_mov_b32_e32 v74, v129
	v_mov_b32_e32 v75, v129
	v_mov_b32_e32 v76, v129
	v_mov_b32_e32 v77, v129
	v_mov_b32_e32 v78, v129
	v_mov_b32_e32 v79, v129
	v_mov_b32_e32 v80, 0
	v_mov_b32_e32 v81, v129
	v_mov_b32_e32 v82, v129
	v_mov_b32_e32 v83, v129
	v_mov_b32_e32 v84, v129
	v_mov_b32_e32 v85, v129
	v_mov_b32_e32 v86, v129
	v_mov_b32_e32 v87, v129
	v_mov_b32_e32 v88, v129
	v_mov_b32_e32 v89, v129
	v_mov_b32_e32 v90, v129
	v_mov_b32_e32 v91, v129
	v_mov_b32_e32 v92, v129
	v_mov_b32_e32 v93, v129
	v_mov_b32_e32 v94, v129
	v_mov_b32_e32 v95, v129
	v_mov_b32_e32 v96, 0
	v_mov_b32_e32 v97, v129
	v_mov_b32_e32 v98, v129
	v_mov_b32_e32 v99, v129
	v_mov_b32_e32 v100, v129
	v_mov_b32_e32 v101, v129
	v_mov_b32_e32 v102, v129
	v_mov_b32_e32 v103, v129
	v_mov_b32_e32 v104, v129
	v_mov_b32_e32 v105, v129
	v_mov_b32_e32 v106, v129
	v_mov_b32_e32 v107, v129
	v_mov_b32_e32 v108, v129
	v_mov_b32_e32 v109, v129
	v_mov_b32_e32 v110, v129
	v_mov_b32_e32 v111, v129
	v_mov_b32_e32 v112, 0
	v_mov_b32_e32 v113, v129
	v_mov_b32_e32 v114, v129
	v_mov_b32_e32 v115, v129
	v_mov_b32_e32 v116, v129
	v_mov_b32_e32 v117, v129
	v_mov_b32_e32 v118, v129
	v_mov_b32_e32 v119, v129
	v_mov_b32_e32 v120, v129
	v_mov_b32_e32 v121, v129
	v_mov_b32_e32 v122, v129
	v_mov_b32_e32 v123, v129
	v_mov_b32_e32 v124, v129
	v_mov_b32_e32 v125, v129
	v_mov_b32_e32 v126, v129
	v_mov_b32_e32 v127, v129
	s_waitcnt vmcnt(0) lgkmcnt(0)
	s_barrier
	v_readfirstlane_b32 s48, v150
	s_sub_u32 s48, s48, 16
	s_mov_b32 s49, 0
	s_mov_b32 s50, 0x8000
	s_mov_b32 s52, 0x10000
	v_and_b32_e32 v170, 63, v186
	v_and_b32_e32 v171, 15, v170
	v_lshrrev_b32_e32 v166, 4, v170
	v_bfe_u32 v167, v170, 1, 3
	v_xor_b32_e32 v142, v166, v167
	v_or_b32_e32 v166, 4, v166
	v_xor_b32_e32 v143, v166, v167
	v_lshlrev_b32_e32 v142, 4, v142
	v_lshlrev_b32_e32 v143, 4, v143
	v_lshl_add_u32 v142, v171, 7, v142
	v_lshl_add_u32 v143, v171, 7, v143
	v_bfe_u32 v166, v186, 6, 2
	v_lshl_add_u32 v144, v166, 13, v142
	v_lshl_add_u32 v145, v166, 13, v143
	v_lshrrev_b32_e32 v166, 8, v186
	v_lshl_add_u32 v142, v166, 14, v142
	v_lshl_add_u32 v143, v166, 14, v143
	v_readfirstlane_b32 s56, v138
	v_readfirstlane_b32 s57, v139
	s_and_b32 s53, s48, 0x400
	s_lshr_b32 s53, s53, 4
	s_sub_u32 s56, s56, s53
	s_subb_u32 s57, s57, 0
	v_subrev_u32_e32 v168, s56, v138
	s_add_u32 s62, s56, s24
	s_addc_u32 s63, s57, s25
	s_add_u32 s60, s56, s22
	s_addc_u32 s61, s57, s23
	s_add_u32 s58, s56, s20
	s_addc_u32 s59, s57, s21
	s_add_u32 s56, s56, s18
	s_addc_u32 s57, s57, s19
	v_readfirstlane_b32 s64, v140
	v_readfirstlane_b32 s65, v141
	s_and_b32 s53, s48, 0x400
	s_lshr_b32 s53, s53, 4
	s_sub_u32 s64, s64, s53
	s_subb_u32 s65, s65, 0
	v_subrev_u32_e32 v169, s64, v140
	s_add_u32 s70, s64, s24
	s_addc_u32 s71, s65, s25
	s_add_u32 s68, s64, s22
	s_addc_u32 s69, s65, s23
	s_add_u32 s66, s64, s20
	s_addc_u32 s67, s65, s21
	s_add_u32 s64, s64, s18
	s_addc_u32 s65, s65, s19
	s_add_u32 m0, s52, s48
	s_nop 0
	global_load_lds_dwordx4 v168, s[56:57]
	s_add_u32 s56, s56, 0x80
	s_addc_u32 s57, s57, 0
	s_add_u32 s53, s52, s48
	s_add_u32 m0, s53, 0x2000
	s_nop 0
	global_load_lds_dwordx4 v168, s[58:59]
	s_add_u32 s58, s58, 0x80
	s_addc_u32 s59, s59, 0
	s_add_u32 s53, s52, s48
	s_add_u32 m0, s53, 0x4000
	s_nop 0
	global_load_lds_dwordx4 v168, s[60:61]
	s_add_u32 s60, s60, 0x80
	s_addc_u32 s61, s61, 0
	s_add_u32 s53, s52, s48
	s_add_u32 m0, s53, 0x6000
	s_nop 0
	global_load_lds_dwordx4 v168, s[62:63]
	s_add_u32 s62, s62, 0x80
	s_addc_u32 s63, s63, 0
	v_add_u32_e32 v167, s50, v144
	v_add_u32_e32 v166, s49, v142
	ds_read_b128 v[188:191], v167
	ds_read_b128 v[192:195], v167 offset:2048
	ds_read_b128 v[196:199], v167 offset:4096
	ds_read_b128 v[200:203], v167 offset:6144
	ds_read_b128 v[220:223], v166
	ds_read_b128 v[224:227], v166 offset:2048
	ds_read_b128 v[228:231], v166 offset:4096
	ds_read_b128 v[232:235], v166 offset:6144
.Lg162_loop:
	s_add_u32 s51, s50, 0x10000
	s_sub_u32 s53, s51, 0x28000
	s_cmp_ge_u32 s51, 0x28000
	s_cselect_b32 s51, s53, s51
	s_add_u32 s52, s49, 0x20000
	s_sub_u32 s53, s52, 0x28000
	s_cmp_ge_u32 s52, 0x28000
	s_cselect_b32 s52, s53, s52
	v_add_u32_e32 v167, s50, v145
	s_waitcnt lgkmcnt(4)
	s_waitcnt lgkmcnt(3)
	v_mfma_f32_16x16x32_bf16 v[112:115], v[188:191], v[220:223], v[112:115]
	v_mfma_f32_16x16x32_bf16 v[120:123], v[192:195], v[220:223], v[120:123]
	v_mfma_f32_16x16x32_bf16 v[96:99], v[196:199], v[220:223], v[96:99]
	v_mfma_f32_16x16x32_bf16 v[104:107], v[200:203], v[220:223], v[104:107]
	s_add_u32 m0, s51, s48
	s_nop 0
	global_load_lds_dwordx4 v169, s[64:65]
	s_add_u32 s64, s64, 0x80
	s_addc_u32 s65, s65, 0
	ds_read_b128 v[220:223], v166 offset:8192
	ds_read_b128 v[204:207], v167
	s_waitcnt lgkmcnt(4)
	v_mfma_f32_16x16x32_bf16 v[116:119], v[188:191], v[224:227], v[116:119]
	v_mfma_f32_16x16x32_bf16 v[124:127], v[192:195], v[224:227], v[124:127]
	v_mfma_f32_16x16x32_bf16 v[100:103], v[196:199], v[224:227], v[100:103]
	v_mfma_f32_16x16x32_bf16 v[108:111], v[200:203], v[224:227], v[108:111]
	s_add_u32 s53, s51, s48
	s_add_u32 m0, s53, 0x2000
	s_nop 0
	global_load_lds_dwordx4 v169, s[66:67]
	s_add_u32 s66, s66, 0x80
	s_addc_u32 s67, s67, 0
	ds_read_b128 v[224:227], v166 offset:10240
	ds_read_b128 v[208:211], v167 offset:2048
	s_waitcnt lgkmcnt(5)
	v_mfma_f32_16x16x32_bf16 v[80:83], v[188:191], v[228:231], v[80:83]
	v_mfma_f32_16x16x32_bf16 v[88:91], v[192:195], v[228:231], v[88:91]
	v_mfma_f32_16x16x32_bf16 v[64:67], v[196:199], v[228:231], v[64:67]
	v_mfma_f32_16x16x32_bf16 v[72:75], v[200:203], v[228:231], v[72:75]
	s_add_u32 s53, s51, s48
	s_add_u32 m0, s53, 0x4000
	s_nop 0
	global_load_lds_dwordx4 v169, s[68:69]
	s_add_u32 s68, s68, 0x80
	s_addc_u32 s69, s69, 0
	ds_read_b128 v[228:231], v166 offset:12288
	ds_read_b128 v[212:215], v167 offset:4096
	s_waitcnt lgkmcnt(6)
	v_mfma_f32_16x16x32_bf16 v[84:87], v[188:191], v[232:235], v[84:87]
	v_mfma_f32_16x16x32_bf16 v[92:95], v[192:195], v[232:235], v[92:95]
	v_mfma_f32_16x16x32_bf16 v[68:71], v[196:199], v[232:235], v[68:71]
	v_mfma_f32_16x16x32_bf16 v[76:79], v[200:203], v[232:235], v[76:79]
	s_add_u32 s53, s51, s48
	s_add_u32 m0, s53, 0x6000
	s_nop 0
	global_load_lds_dwordx4 v169, s[70:71]
	s_add_u32 s70, s70, 0x80
	s_addc_u32 s71, s71, 0
	ds_read_b128 v[232:235], v166 offset:14336
	ds_read_b128 v[216:219], v167 offset:6144
	v_add_u32_e32 v166, s49, v143
	s_waitcnt lgkmcnt(7)
	v_mfma_f32_16x16x32_bf16 v[48:51], v[188:191], v[220:223], v[48:51]
	v_mfma_f32_16x16x32_bf16 v[56:59], v[192:195], v[220:223], v[56:59]
	v_mfma_f32_16x16x32_bf16 v[32:35], v[196:199], v[220:223], v[32:35]
	v_mfma_f32_16x16x32_bf16 v[40:43], v[200:203], v[220:223], v[40:43]
	s_add_u32 m0, s52, s48
	s_nop 0
	global_load_lds_dwordx4 v168, s[56:57]
	s_add_u32 s56, s56, 0x80
	s_addc_u32 s57, s57, 0
	ds_read_b128 v[220:223], v166
	s_waitcnt lgkmcnt(6)
	v_mfma_f32_16x16x32_bf16 v[52:55], v[188:191], v[224:227], v[52:55]
	v_mfma_f32_16x16x32_bf16 v[60:63], v[192:195], v[224:227], v[60:63]
	v_mfma_f32_16x16x32_bf16 v[36:39], v[196:199], v[224:227], v[36:39]
	v_mfma_f32_16x16x32_bf16 v[44:47], v[200:203], v[224:227], v[44:47]
	s_add_u32 s53, s52, s48
	s_add_u32 m0, s53, 0x2000
	s_nop 0
	global_load_lds_dwordx4 v168, s[58:59]
	s_add_u32 s58, s58, 0x80
	s_addc_u32 s59, s59, 0
	ds_read_b128 v[224:227], v166 offset:2048
	s_waitcnt lgkmcnt(5)
	v_mfma_f32_16x16x32_bf16 v[16:19], v[188:191], v[228:231], v[16:19]
	v_mfma_f32_16x16x32_bf16 v[24:27], v[192:195], v[228:231], v[24:27]
	v_mfma_f32_16x16x32_bf16 v[0:3], v[196:199], v[228:231], v[0:3]
	v_mfma_f32_16x16x32_bf16 v[8:11], v[200:203], v[228:231], v[8:11]
	s_add_u32 s53, s52, s48
	s_add_u32 m0, s53, 0x4000
	s_nop 0
	global_load_lds_dwordx4 v168, s[60:61]
	s_add_u32 s60, s60, 0x80
	s_addc_u32 s61, s61, 0
	ds_read_b128 v[228:231], v166 offset:4096
	s_waitcnt lgkmcnt(4)
	v_mfma_f32_16x16x32_bf16 v[20:23], v[188:191], v[232:235], v[20:23]
	v_mfma_f32_16x16x32_bf16 v[28:31], v[192:195], v[232:235], v[28:31]
	v_mfma_f32_16x16x32_bf16 v[4:7], v[196:199], v[232:235], v[4:7]
	v_mfma_f32_16x16x32_bf16 v[12:15], v[200:203], v[232:235], v[12:15]
	s_add_u32 s53, s52, s48
	s_add_u32 m0, s53, 0x6000
	s_nop 0
	global_load_lds_dwordx4 v168, s[62:63]
	s_add_u32 s62, s62, 0x80
	s_addc_u32 s63, s63, 0
	ds_read_b128 v[232:235], v166 offset:6144
	s_waitcnt lgkmcnt(4)
	s_waitcnt lgkmcnt(3)
	v_mfma_f32_16x16x32_bf16 v[112:115], v[204:207], v[220:223], v[112:115]
	v_mfma_f32_16x16x32_bf16 v[120:123], v[208:211], v[220:223], v[120:123]
	v_mfma_f32_16x16x32_bf16 v[96:99], v[212:215], v[220:223], v[96:99]
	v_mfma_f32_16x16x32_bf16 v[104:107], v[216:219], v[220:223], v[104:107]
	ds_read_b128 v[220:223], v166 offset:8192
	s_waitcnt lgkmcnt(3)
	v_mfma_f32_16x16x32_bf16 v[116:119], v[204:207], v[224:227], v[116:119]
	v_mfma_f32_16x16x32_bf16 v[124:127], v[208:211], v[224:227], v[124:127]
	v_mfma_f32_16x16x32_bf16 v[100:103], v[212:215], v[224:227], v[100:103]
	v_mfma_f32_16x16x32_bf16 v[108:111], v[216:219], v[224:227], v[108:111]
	ds_read_b128 v[224:227], v166 offset:10240
	s_waitcnt lgkmcnt(3)
	v_mfma_f32_16x16x32_bf16 v[80:83], v[204:207], v[228:231], v[80:83]
	v_mfma_f32_16x16x32_bf16 v[88:91], v[208:211], v[228:231], v[88:91]
	v_mfma_f32_16x16x32_bf16 v[64:67], v[212:215], v[228:231], v[64:67]
	v_mfma_f32_16x16x32_bf16 v[72:75], v[216:219], v[228:231], v[72:75]
	ds_read_b128 v[228:231], v166 offset:12288
	s_waitcnt lgkmcnt(3)
	v_mfma_f32_16x16x32_bf16 v[84:87], v[204:207], v[232:235], v[84:87]
	v_mfma_f32_16x16x32_bf16 v[92:95], v[208:211], v[232:235], v[92:95]
	v_mfma_f32_16x16x32_bf16 v[68:71], v[212:215], v[232:235], v[68:71]
	v_mfma_f32_16x16x32_bf16 v[76:79], v[216:219], v[232:235], v[76:79]
	ds_read_b128 v[232:235], v166 offset:14336
	s_waitcnt lgkmcnt(3)
	v_mfma_f32_16x16x32_bf16 v[48:51], v[204:207], v[220:223], v[48:51]
	v_mfma_f32_16x16x32_bf16 v[56:59], v[208:211], v[220:223], v[56:59]
	v_mfma_f32_16x16x32_bf16 v[32:35], v[212:215], v[220:223], v[32:35]
	v_mfma_f32_16x16x32_bf16 v[40:43], v[216:219], v[220:223], v[40:43]
	s_waitcnt lgkmcnt(2)
	v_mfma_f32_16x16x32_bf16 v[52:55], v[204:207], v[224:227], v[52:55]
	v_mfma_f32_16x16x32_bf16 v[60:63], v[208:211], v[224:227], v[60:63]
	v_mfma_f32_16x16x32_bf16 v[36:39], v[212:215], v[224:227], v[36:39]
	v_mfma_f32_16x16x32_bf16 v[44:47], v[216:219], v[224:227], v[44:47]
	s_waitcnt lgkmcnt(0)
	s_add_u32 s28, s28, 0x80
	s_addc_u32 s29, s29, 0
	s_add_u32 s49, s49, 0x10000
	s_sub_u32 s53, s49, 0x28000
	s_cmp_ge_u32 s49, 0x28000
	s_cselect_b32 s49, s53, s49
	s_mov_b32 s50, s51
	s_waitcnt vmcnt(4)
	s_barrier
	v_add_u32_e32 v167, s50, v144
	v_add_u32_e32 v166, s49, v142
	ds_read_b128 v[188:191], v167
	ds_read_b128 v[192:195], v167 offset:2048
	ds_read_b128 v[196:199], v167 offset:4096
	ds_read_b128 v[200:203], v167 offset:6144
	ds_read_b128 v[220:223], v166
	ds_read_b128 v[224:227], v166 offset:2048
	v_mfma_f32_16x16x32_bf16 v[16:19], v[204:207], v[228:231], v[16:19]
	v_mfma_f32_16x16x32_bf16 v[24:27], v[208:211], v[228:231], v[24:27]
	v_mfma_f32_16x16x32_bf16 v[0:3], v[212:215], v[228:231], v[0:3]
	v_mfma_f32_16x16x32_bf16 v[8:11], v[216:219], v[228:231], v[8:11]
	ds_read_b128 v[228:231], v166 offset:4096
	v_mfma_f32_16x16x32_bf16 v[20:23], v[204:207], v[232:235], v[20:23]
	v_mfma_f32_16x16x32_bf16 v[28:31], v[208:211], v[232:235], v[28:31]
	v_mfma_f32_16x16x32_bf16 v[4:7], v[212:215], v[232:235], v[4:7]
	v_mfma_f32_16x16x32_bf16 v[12:15], v[216:219], v[232:235], v[12:15]
	ds_read_b128 v[232:235], v166 offset:6144
	s_cmpk_lg_i32 s28, 0xf00
	s_cbranch_scc1 .Lg162_loop
	s_add_u32 s51, s50, 0x10000
	s_sub_u32 s53, s51, 0x28000
	s_cmp_ge_u32 s51, 0x28000
	s_cselect_b32 s51, s53, s51
	v_add_u32_e32 v167, s50, v145
	s_waitcnt lgkmcnt(4)
	s_waitcnt lgkmcnt(3)
	v_mfma_f32_16x16x32_bf16 v[112:115], v[188:191], v[220:223], v[112:115]
	v_mfma_f32_16x16x32_bf16 v[120:123], v[192:195], v[220:223], v[120:123]
	v_mfma_f32_16x16x32_bf16 v[96:99], v[196:199], v[220:223], v[96:99]
	v_mfma_f32_16x16x32_bf16 v[104:107], v[200:203], v[220:223], v[104:107]
	s_add_u32 m0, s51, s48
	s_nop 0
	global_load_lds_dwordx4 v169, s[64:65]
	s_add_u32 s64, s64, 0x80
	s_addc_u32 s65, s65, 0
	ds_read_b128 v[220:223], v166 offset:8192
	ds_read_b128 v[204:207], v167
	s_waitcnt lgkmcnt(4)
	v_mfma_f32_16x16x32_bf16 v[116:119], v[188:191], v[224:227], v[116:119]
	v_mfma_f32_16x16x32_bf16 v[124:127], v[192:195], v[224:227], v[124:127]
	v_mfma_f32_16x16x32_bf16 v[100:103], v[196:199], v[224:227], v[100:103]
	v_mfma_f32_16x16x32_bf16 v[108:111], v[200:203], v[224:227], v[108:111]
	s_add_u32 s53, s51, s48
	s_add_u32 m0, s53, 0x2000
	s_nop 0
	global_load_lds_dwordx4 v169, s[66:67]
	s_add_u32 s66, s66, 0x80
	s_addc_u32 s67, s67, 0
	ds_read_b128 v[224:227], v166 offset:10240
	ds_read_b128 v[208:211], v167 offset:2048
	s_waitcnt lgkmcnt(5)
	v_mfma_f32_16x16x32_bf16 v[80:83], v[188:191], v[228:231], v[80:83]
	v_mfma_f32_16x16x32_bf16 v[88:91], v[192:195], v[228:231], v[88:91]
	v_mfma_f32_16x16x32_bf16 v[64:67], v[196:199], v[228:231], v[64:67]
	v_mfma_f32_16x16x32_bf16 v[72:75], v[200:203], v[228:231], v[72:75]
	s_add_u32 s53, s51, s48
	s_add_u32 m0, s53, 0x4000
	s_nop 0
	global_load_lds_dwordx4 v169, s[68:69]
	s_add_u32 s68, s68, 0x80
	s_addc_u32 s69, s69, 0
	ds_read_b128 v[228:231], v166 offset:12288
	ds_read_b128 v[212:215], v167 offset:4096
	s_waitcnt lgkmcnt(6)
	v_mfma_f32_16x16x32_bf16 v[84:87], v[188:191], v[232:235], v[84:87]
	v_mfma_f32_16x16x32_bf16 v[92:95], v[192:195], v[232:235], v[92:95]
	v_mfma_f32_16x16x32_bf16 v[68:71], v[196:199], v[232:235], v[68:71]
	v_mfma_f32_16x16x32_bf16 v[76:79], v[200:203], v[232:235], v[76:79]
	s_add_u32 s53, s51, s48
	s_add_u32 m0, s53, 0x6000
	s_nop 0
	global_load_lds_dwordx4 v169, s[70:71]
	s_add_u32 s70, s70, 0x80
	s_addc_u32 s71, s71, 0
	ds_read_b128 v[232:235], v166 offset:14336
	ds_read_b128 v[216:219], v167 offset:6144
	v_add_u32_e32 v166, s49, v143
	s_waitcnt lgkmcnt(7)
	v_mfma_f32_16x16x32_bf16 v[48:51], v[188:191], v[220:223], v[48:51]
	v_mfma_f32_16x16x32_bf16 v[56:59], v[192:195], v[220:223], v[56:59]
	v_mfma_f32_16x16x32_bf16 v[32:35], v[196:199], v[220:223], v[32:35]
	v_mfma_f32_16x16x32_bf16 v[40:43], v[200:203], v[220:223], v[40:43]
	ds_read_b128 v[220:223], v166
	s_waitcnt lgkmcnt(6)
	v_mfma_f32_16x16x32_bf16 v[52:55], v[188:191], v[224:227], v[52:55]
	v_mfma_f32_16x16x32_bf16 v[60:63], v[192:195], v[224:227], v[60:63]
	v_mfma_f32_16x16x32_bf16 v[36:39], v[196:199], v[224:227], v[36:39]
	v_mfma_f32_16x16x32_bf16 v[44:47], v[200:203], v[224:227], v[44:47]
	ds_read_b128 v[224:227], v166 offset:2048
	s_waitcnt lgkmcnt(5)
	v_mfma_f32_16x16x32_bf16 v[16:19], v[188:191], v[228:231], v[16:19]
	v_mfma_f32_16x16x32_bf16 v[24:27], v[192:195], v[228:231], v[24:27]
	v_mfma_f32_16x16x32_bf16 v[0:3], v[196:199], v[228:231], v[0:3]
	v_mfma_f32_16x16x32_bf16 v[8:11], v[200:203], v[228:231], v[8:11]
	ds_read_b128 v[228:231], v166 offset:4096
	s_waitcnt lgkmcnt(4)
	v_mfma_f32_16x16x32_bf16 v[20:23], v[188:191], v[232:235], v[20:23]
	v_mfma_f32_16x16x32_bf16 v[28:31], v[192:195], v[232:235], v[28:31]
	v_mfma_f32_16x16x32_bf16 v[4:7], v[196:199], v[232:235], v[4:7]
	v_mfma_f32_16x16x32_bf16 v[12:15], v[200:203], v[232:235], v[12:15]
	ds_read_b128 v[232:235], v166 offset:6144
	s_waitcnt lgkmcnt(4)
	s_waitcnt lgkmcnt(3)
	v_mfma_f32_16x16x32_bf16 v[112:115], v[204:207], v[220:223], v[112:115]
	v_mfma_f32_16x16x32_bf16 v[120:123], v[208:211], v[220:223], v[120:123]
	v_mfma_f32_16x16x32_bf16 v[96:99], v[212:215], v[220:223], v[96:99]
	v_mfma_f32_16x16x32_bf16 v[104:107], v[216:219], v[220:223], v[104:107]
	ds_read_b128 v[220:223], v166 offset:8192
	s_waitcnt lgkmcnt(3)
	v_mfma_f32_16x16x32_bf16 v[116:119], v[204:207], v[224:227], v[116:119]
	v_mfma_f32_16x16x32_bf16 v[124:127], v[208:211], v[224:227], v[124:127]
	v_mfma_f32_16x16x32_bf16 v[100:103], v[212:215], v[224:227], v[100:103]
	v_mfma_f32_16x16x32_bf16 v[108:111], v[216:219], v[224:227], v[108:111]
	ds_read_b128 v[224:227], v166 offset:10240
	s_waitcnt lgkmcnt(3)
	v_mfma_f32_16x16x32_bf16 v[80:83], v[204:207], v[228:231], v[80:83]
	v_mfma_f32_16x16x32_bf16 v[88:91], v[208:211], v[228:231], v[88:91]
	v_mfma_f32_16x16x32_bf16 v[64:67], v[212:215], v[228:231], v[64:67]
	v_mfma_f32_16x16x32_bf16 v[72:75], v[216:219], v[228:231], v[72:75]
	ds_read_b128 v[228:231], v166 offset:12288
	s_waitcnt lgkmcnt(3)
	v_mfma_f32_16x16x32_bf16 v[84:87], v[204:207], v[232:235], v[84:87]
	v_mfma_f32_16x16x32_bf16 v[92:95], v[208:211], v[232:235], v[92:95]
	v_mfma_f32_16x16x32_bf16 v[68:71], v[212:215], v[232:235], v[68:71]
	v_mfma_f32_16x16x32_bf16 v[76:79], v[216:219], v[232:235], v[76:79]
	ds_read_b128 v[232:235], v166 offset:14336
	s_waitcnt lgkmcnt(3)
	v_mfma_f32_16x16x32_bf16 v[48:51], v[204:207], v[220:223], v[48:51]
	v_mfma_f32_16x16x32_bf16 v[56:59], v[208:211], v[220:223], v[56:59]
	v_mfma_f32_16x16x32_bf16 v[32:35], v[212:215], v[220:223], v[32:35]
	v_mfma_f32_16x16x32_bf16 v[40:43], v[216:219], v[220:223], v[40:43]
	s_waitcnt lgkmcnt(2)
	v_mfma_f32_16x16x32_bf16 v[52:55], v[204:207], v[224:227], v[52:55]
	v_mfma_f32_16x16x32_bf16 v[60:63], v[208:211], v[224:227], v[60:63]
	v_mfma_f32_16x16x32_bf16 v[36:39], v[212:215], v[224:227], v[36:39]
	v_mfma_f32_16x16x32_bf16 v[44:47], v[216:219], v[224:227], v[44:47]
	s_waitcnt lgkmcnt(0)
	s_add_u32 s28, s28, 0x80
	s_addc_u32 s29, s29, 0
	s_add_u32 s49, s49, 0x10000
	s_sub_u32 s53, s49, 0x28000
	s_cmp_ge_u32 s49, 0x28000
	s_cselect_b32 s49, s53, s49
	s_mov_b32 s50, s51
	s_waitcnt vmcnt(0)
	s_barrier
	v_add_u32_e32 v167, s50, v144
	v_add_u32_e32 v166, s49, v142
	ds_read_b128 v[188:191], v167
	ds_read_b128 v[192:195], v167 offset:2048
	ds_read_b128 v[196:199], v167 offset:4096
	ds_read_b128 v[200:203], v167 offset:6144
	ds_read_b128 v[220:223], v166
	ds_read_b128 v[224:227], v166 offset:2048
	v_mfma_f32_16x16x32_bf16 v[16:19], v[204:207], v[228:231], v[16:19]
	v_mfma_f32_16x16x32_bf16 v[24:27], v[208:211], v[228:231], v[24:27]
	v_mfma_f32_16x16x32_bf16 v[0:3], v[212:215], v[228:231], v[0:3]
	v_mfma_f32_16x16x32_bf16 v[8:11], v[216:219], v[228:231], v[8:11]
	ds_read_b128 v[228:231], v166 offset:4096
	v_mfma_f32_16x16x32_bf16 v[20:23], v[204:207], v[232:235], v[20:23]
	v_mfma_f32_16x16x32_bf16 v[28:31], v[208:211], v[232:235], v[28:31]
	v_mfma_f32_16x16x32_bf16 v[4:7], v[212:215], v[232:235], v[4:7]
	v_mfma_f32_16x16x32_bf16 v[12:15], v[216:219], v[232:235], v[12:15]
	ds_read_b128 v[232:235], v166 offset:6144
	v_add_u32_e32 v167, s50, v145
	s_waitcnt lgkmcnt(4)
	s_waitcnt lgkmcnt(3)
	v_mfma_f32_16x16x32_bf16 v[112:115], v[188:191], v[220:223], v[112:115]
	v_mfma_f32_16x16x32_bf16 v[120:123], v[192:195], v[220:223], v[120:123]
	v_mfma_f32_16x16x32_bf16 v[96:99], v[196:199], v[220:223], v[96:99]
	v_mfma_f32_16x16x32_bf16 v[104:107], v[200:203], v[220:223], v[104:107]
	ds_read_b128 v[220:223], v166 offset:8192
	ds_read_b128 v[204:207], v167
	s_waitcnt lgkmcnt(4)
	v_mfma_f32_16x16x32_bf16 v[116:119], v[188:191], v[224:227], v[116:119]
	v_mfma_f32_16x16x32_bf16 v[124:127], v[192:195], v[224:227], v[124:127]
	v_mfma_f32_16x16x32_bf16 v[100:103], v[196:199], v[224:227], v[100:103]
	v_mfma_f32_16x16x32_bf16 v[108:111], v[200:203], v[224:227], v[108:111]
	ds_read_b128 v[224:227], v166 offset:10240
	ds_read_b128 v[208:211], v167 offset:2048
	s_waitcnt lgkmcnt(5)
	v_mfma_f32_16x16x32_bf16 v[80:83], v[188:191], v[228:231], v[80:83]
	v_mfma_f32_16x16x32_bf16 v[88:91], v[192:195], v[228:231], v[88:91]
	v_mfma_f32_16x16x32_bf16 v[64:67], v[196:199], v[228:231], v[64:67]
	v_mfma_f32_16x16x32_bf16 v[72:75], v[200:203], v[228:231], v[72:75]
	ds_read_b128 v[228:231], v166 offset:12288
	ds_read_b128 v[212:215], v167 offset:4096
	s_waitcnt lgkmcnt(6)
	v_mfma_f32_16x16x32_bf16 v[84:87], v[188:191], v[232:235], v[84:87]
	v_mfma_f32_16x16x32_bf16 v[92:95], v[192:195], v[232:235], v[92:95]
	v_mfma_f32_16x16x32_bf16 v[68:71], v[196:199], v[232:235], v[68:71]
	v_mfma_f32_16x16x32_bf16 v[76:79], v[200:203], v[232:235], v[76:79]
	ds_read_b128 v[232:235], v166 offset:14336
	ds_read_b128 v[216:219], v167 offset:6144
	v_add_u32_e32 v166, s49, v143
	s_waitcnt lgkmcnt(7)
	v_mfma_f32_16x16x32_bf16 v[48:51], v[188:191], v[220:223], v[48:51]
	v_mfma_f32_16x16x32_bf16 v[56:59], v[192:195], v[220:223], v[56:59]
	v_mfma_f32_16x16x32_bf16 v[32:35], v[196:199], v[220:223], v[32:35]
	v_mfma_f32_16x16x32_bf16 v[40:43], v[200:203], v[220:223], v[40:43]
	ds_read_b128 v[220:223], v166
	s_waitcnt lgkmcnt(6)
	v_mfma_f32_16x16x32_bf16 v[52:55], v[188:191], v[224:227], v[52:55]
	v_mfma_f32_16x16x32_bf16 v[60:63], v[192:195], v[224:227], v[60:63]
	v_mfma_f32_16x16x32_bf16 v[36:39], v[196:199], v[224:227], v[36:39]
	v_mfma_f32_16x16x32_bf16 v[44:47], v[200:203], v[224:227], v[44:47]
	ds_read_b128 v[224:227], v166 offset:2048
	s_waitcnt lgkmcnt(5)
	v_mfma_f32_16x16x32_bf16 v[16:19], v[188:191], v[228:231], v[16:19]
	v_mfma_f32_16x16x32_bf16 v[24:27], v[192:195], v[228:231], v[24:27]
	v_mfma_f32_16x16x32_bf16 v[0:3], v[196:199], v[228:231], v[0:3]
	v_mfma_f32_16x16x32_bf16 v[8:11], v[200:203], v[228:231], v[8:11]
	ds_read_b128 v[228:231], v166 offset:4096
	s_waitcnt lgkmcnt(4)
	v_mfma_f32_16x16x32_bf16 v[20:23], v[188:191], v[232:235], v[20:23]
	v_mfma_f32_16x16x32_bf16 v[28:31], v[192:195], v[232:235], v[28:31]
	v_mfma_f32_16x16x32_bf16 v[4:7], v[196:199], v[232:235], v[4:7]
	v_mfma_f32_16x16x32_bf16 v[12:15], v[200:203], v[232:235], v[12:15]
	ds_read_b128 v[232:235], v166 offset:6144
	s_waitcnt lgkmcnt(4)
	s_waitcnt lgkmcnt(3)
	v_mfma_f32_16x16x32_bf16 v[112:115], v[204:207], v[220:223], v[112:115]
	v_mfma_f32_16x16x32_bf16 v[120:123], v[208:211], v[220:223], v[120:123]
	v_mfma_f32_16x16x32_bf16 v[96:99], v[212:215], v[220:223], v[96:99]
	v_mfma_f32_16x16x32_bf16 v[104:107], v[216:219], v[220:223], v[104:107]
	ds_read_b128 v[220:223], v166 offset:8192
	s_waitcnt lgkmcnt(3)
	v_mfma_f32_16x16x32_bf16 v[116:119], v[204:207], v[224:227], v[116:119]
	v_mfma_f32_16x16x32_bf16 v[124:127], v[208:211], v[224:227], v[124:127]
	v_mfma_f32_16x16x32_bf16 v[100:103], v[212:215], v[224:227], v[100:103]
	v_mfma_f32_16x16x32_bf16 v[108:111], v[216:219], v[224:227], v[108:111]
	ds_read_b128 v[224:227], v166 offset:10240
	s_waitcnt lgkmcnt(3)
	v_mfma_f32_16x16x32_bf16 v[80:83], v[204:207], v[228:231], v[80:83]
	v_mfma_f32_16x16x32_bf16 v[88:91], v[208:211], v[228:231], v[88:91]
	v_mfma_f32_16x16x32_bf16 v[64:67], v[212:215], v[228:231], v[64:67]
	v_mfma_f32_16x16x32_bf16 v[72:75], v[216:219], v[228:231], v[72:75]
	ds_read_b128 v[228:231], v166 offset:12288
	s_waitcnt lgkmcnt(3)
	v_mfma_f32_16x16x32_bf16 v[84:87], v[204:207], v[232:235], v[84:87]
	v_mfma_f32_16x16x32_bf16 v[92:95], v[208:211], v[232:235], v[92:95]
	v_mfma_f32_16x16x32_bf16 v[68:71], v[212:215], v[232:235], v[68:71]
	v_mfma_f32_16x16x32_bf16 v[76:79], v[216:219], v[232:235], v[76:79]
	ds_read_b128 v[232:235], v166 offset:14336
	s_waitcnt lgkmcnt(3)
	v_mfma_f32_16x16x32_bf16 v[48:51], v[204:207], v[220:223], v[48:51]
	v_mfma_f32_16x16x32_bf16 v[56:59], v[208:211], v[220:223], v[56:59]
	v_mfma_f32_16x16x32_bf16 v[32:35], v[212:215], v[220:223], v[32:35]
	v_mfma_f32_16x16x32_bf16 v[40:43], v[216:219], v[220:223], v[40:43]
	s_waitcnt lgkmcnt(2)
	v_mfma_f32_16x16x32_bf16 v[52:55], v[204:207], v[224:227], v[52:55]
	v_mfma_f32_16x16x32_bf16 v[60:63], v[208:211], v[224:227], v[60:63]
	v_mfma_f32_16x16x32_bf16 v[36:39], v[212:215], v[224:227], v[36:39]
	v_mfma_f32_16x16x32_bf16 v[44:47], v[216:219], v[224:227], v[44:47]
	s_waitcnt lgkmcnt(0)
	s_waitcnt vmcnt(0)
	s_barrier
	v_mfma_f32_16x16x32_bf16 v[16:19], v[204:207], v[228:231], v[16:19]
	v_mfma_f32_16x16x32_bf16 v[24:27], v[208:211], v[228:231], v[24:27]
	v_mfma_f32_16x16x32_bf16 v[0:3], v[212:215], v[228:231], v[0:3]
	v_mfma_f32_16x16x32_bf16 v[8:11], v[216:219], v[228:231], v[8:11]
	v_mfma_f32_16x16x32_bf16 v[20:23], v[204:207], v[232:235], v[20:23]
	v_mfma_f32_16x16x32_bf16 v[28:31], v[208:211], v[232:235], v[28:31]
	v_mfma_f32_16x16x32_bf16 v[4:7], v[212:215], v[232:235], v[4:7]
	v_mfma_f32_16x16x32_bf16 v[12:15], v[216:219], v[232:235], v[12:15]
	s_nop 15
	v_permlane16_swap_b32_e32 v112, v116
	v_permlane16_swap_b32_e32 v113, v117
	v_permlane16_swap_b32_e32 v114, v118
	v_permlane16_swap_b32_e32 v115, v119
	v_permlane16_swap_b32_e32 v120, v124
	v_permlane16_swap_b32_e32 v121, v125
	v_permlane16_swap_b32_e32 v122, v126
	v_permlane16_swap_b32_e32 v123, v127
	v_permlane16_swap_b32_e32 v96, v100
	v_permlane16_swap_b32_e32 v97, v101
	v_permlane16_swap_b32_e32 v98, v102
	v_permlane16_swap_b32_e32 v99, v103
	v_permlane16_swap_b32_e32 v104, v108
	v_permlane16_swap_b32_e32 v105, v109
	v_permlane16_swap_b32_e32 v106, v110
	v_permlane16_swap_b32_e32 v107, v111
	v_permlane16_swap_b32_e32 v80, v84
	v_permlane16_swap_b32_e32 v81, v85
	v_permlane16_swap_b32_e32 v82, v86
	v_permlane16_swap_b32_e32 v83, v87
	v_permlane16_swap_b32_e32 v88, v92
	v_permlane16_swap_b32_e32 v89, v93
	v_permlane16_swap_b32_e32 v90, v94
	v_permlane16_swap_b32_e32 v91, v95
	v_permlane16_swap_b32_e32 v64, v68
	v_permlane16_swap_b32_e32 v65, v69
	v_permlane16_swap_b32_e32 v66, v70
	v_permlane16_swap_b32_e32 v67, v71
	v_permlane16_swap_b32_e32 v72, v76
	v_permlane16_swap_b32_e32 v73, v77
	v_permlane16_swap_b32_e32 v74, v78
	v_permlane16_swap_b32_e32 v75, v79
	v_permlane16_swap_b32_e32 v48, v52
	v_permlane16_swap_b32_e32 v49, v53
	v_permlane16_swap_b32_e32 v50, v54
	v_permlane16_swap_b32_e32 v51, v55
	v_permlane16_swap_b32_e32 v56, v60
	v_permlane16_swap_b32_e32 v57, v61
	v_permlane16_swap_b32_e32 v58, v62
	v_permlane16_swap_b32_e32 v59, v63
	v_permlane16_swap_b32_e32 v32, v36
	v_permlane16_swap_b32_e32 v33, v37
	v_permlane16_swap_b32_e32 v34, v38
	v_permlane16_swap_b32_e32 v35, v39
	v_permlane16_swap_b32_e32 v40, v44
	v_permlane16_swap_b32_e32 v41, v45
	v_permlane16_swap_b32_e32 v42, v46
	v_permlane16_swap_b32_e32 v43, v47
	v_permlane16_swap_b32_e32 v16, v20
	v_permlane16_swap_b32_e32 v17, v21
	v_permlane16_swap_b32_e32 v18, v22
	v_permlane16_swap_b32_e32 v19, v23
	v_permlane16_swap_b32_e32 v24, v28
	v_permlane16_swap_b32_e32 v25, v29
	v_permlane16_swap_b32_e32 v26, v30
	v_permlane16_swap_b32_e32 v27, v31
	v_permlane16_swap_b32_e32 v0, v4
	v_permlane16_swap_b32_e32 v1, v5
	v_permlane16_swap_b32_e32 v2, v6
	v_permlane16_swap_b32_e32 v3, v7
	v_permlane16_swap_b32_e32 v8, v12
	v_permlane16_swap_b32_e32 v9, v13
	v_permlane16_swap_b32_e32 v10, v14
	v_permlane16_swap_b32_e32 v11, v15
	v_permlane32_swap_b32_e32 v112, v116
	v_permlane32_swap_b32_e32 v113, v117
	v_permlane32_swap_b32_e32 v114, v118
	v_permlane32_swap_b32_e32 v115, v119
	v_permlane32_swap_b32_e32 v120, v124
	v_permlane32_swap_b32_e32 v121, v125
	v_permlane32_swap_b32_e32 v122, v126
	v_permlane32_swap_b32_e32 v123, v127
	v_permlane32_swap_b32_e32 v96, v100
	v_permlane32_swap_b32_e32 v97, v101
	v_permlane32_swap_b32_e32 v98, v102
	v_permlane32_swap_b32_e32 v99, v103
	v_permlane32_swap_b32_e32 v104, v108
	v_permlane32_swap_b32_e32 v105, v109
	v_permlane32_swap_b32_e32 v106, v110
	v_permlane32_swap_b32_e32 v107, v111
	v_permlane32_swap_b32_e32 v80, v84
	v_permlane32_swap_b32_e32 v81, v85
	v_permlane32_swap_b32_e32 v82, v86
	v_permlane32_swap_b32_e32 v83, v87
	v_permlane32_swap_b32_e32 v88, v92
	v_permlane32_swap_b32_e32 v89, v93
	v_permlane32_swap_b32_e32 v90, v94
	v_permlane32_swap_b32_e32 v91, v95
	v_permlane32_swap_b32_e32 v64, v68
	v_permlane32_swap_b32_e32 v65, v69
	v_permlane32_swap_b32_e32 v66, v70
	v_permlane32_swap_b32_e32 v67, v71
	v_permlane32_swap_b32_e32 v72, v76
	v_permlane32_swap_b32_e32 v73, v77
	v_permlane32_swap_b32_e32 v74, v78
	v_permlane32_swap_b32_e32 v75, v79
	v_permlane32_swap_b32_e32 v48, v52
	v_permlane32_swap_b32_e32 v49, v53
	v_permlane32_swap_b32_e32 v50, v54
	v_permlane32_swap_b32_e32 v51, v55
	v_permlane32_swap_b32_e32 v56, v60
	v_permlane32_swap_b32_e32 v57, v61
	v_permlane32_swap_b32_e32 v58, v62
	v_permlane32_swap_b32_e32 v59, v63
	v_permlane32_swap_b32_e32 v32, v36
	v_permlane32_swap_b32_e32 v33, v37
	v_permlane32_swap_b32_e32 v34, v38
	v_permlane32_swap_b32_e32 v35, v39
	v_permlane32_swap_b32_e32 v40, v44
	v_permlane32_swap_b32_e32 v41, v45
	v_permlane32_swap_b32_e32 v42, v46
	v_permlane32_swap_b32_e32 v43, v47
	v_permlane32_swap_b32_e32 v16, v20
	v_permlane32_swap_b32_e32 v17, v21
	v_permlane32_swap_b32_e32 v18, v22
	v_permlane32_swap_b32_e32 v19, v23
	v_permlane32_swap_b32_e32 v24, v28
	v_permlane32_swap_b32_e32 v25, v29
	v_permlane32_swap_b32_e32 v26, v30
	v_permlane32_swap_b32_e32 v27, v31
	v_permlane32_swap_b32_e32 v0, v4
	v_permlane32_swap_b32_e32 v1, v5
	v_permlane32_swap_b32_e32 v2, v6
	v_permlane32_swap_b32_e32 v3, v7
	v_permlane32_swap_b32_e32 v8, v12
	v_permlane32_swap_b32_e32 v9, v13
	v_permlane32_swap_b32_e32 v10, v14
	v_permlane32_swap_b32_e32 v11, v15
	s_nop 1
	s_branch .LBB0_163

.LBB0_198:
	s_ashr_i32 s27, s30, 2
	s_and_b32 s27, s27, -8
	s_or_b32 s33, s27, s3
	s_ashr_i32 s27, s33, 31
	s_lshr_b32 s27, s27, 29
	s_add_i32 s27, s33, s27
	s_ashr_i32 s46, s27, 3
	s_bfe_u32 s26, s30, 0x20003
	s_and_b32 s27, s27, 0x1ffff8
	s_lshl_b32 s47, s46, 2
	s_lshl_b32 s29, s26, 8
	s_sub_i32 s27, s33, s27
	s_or_b32 s26, s47, s26
	s_lshl_b32 s47, s30, 8
	s_lshl_b32 s27, s27, 11
	s_and_b32 s47, s47, 0x700
	s_or_b32 s27, s27, s47
	v_add_u32_e32 v0, s27, v142
	v_ashrrev_i32_e32 v1, 31, v0
	v_lshl_add_u32 v2, s26, 8, v142
	v_lshlrev_b64 v[0:1], 12, v[0:1]
	v_ashrrev_i32_e32 v3, 31, v2
	v_readfirstlane_b32 s47, v143
	v_add_u32_e32 v4, 0x8000, v143
	v_lshl_add_u64 v[0:1], v[130:131], 0, v[0:1]
	v_lshlrev_b64 v[2:3], 12, v[2:3]
	s_add_i32 m0, s47, -16
	v_readfirstlane_b32 s47, v4
	v_add_u32_e32 v6, 0x2000, v143
	v_lshl_add_u64 v[2:3], v[132:133], 0, v[2:3]
	global_load_lds_dwordx4 v[0:1], off
	s_add_i32 m0, s47, -16
	v_readfirstlane_b32 s47, v6
	v_add_u32_e32 v6, 0xa000, v143
	global_load_lds_dwordx4 v[2:3], off
	v_lshl_add_u64 v[4:5], v[0:1], 0, s[12:13]
	s_add_i32 m0, s47, -16
	v_readfirstlane_b32 s47, v6
	v_add_u32_e32 v6, 0x4000, v143
	global_load_lds_dwordx4 v[4:5], off
	v_lshl_add_u64 v[4:5], v[2:3], 0, s[12:13]
	s_add_i32 m0, s47, -16
	v_readfirstlane_b32 s47, v6
	v_add_u32_e32 v6, 0xc000, v143
	global_load_lds_dwordx4 v[4:5], off
	v_lshl_add_u64 v[4:5], v[0:1], 0, s[14:15]
	s_add_i32 m0, s47, -16
	v_readfirstlane_b32 s47, v6
	global_load_lds_dwordx4 v[4:5], off
	v_lshl_add_u64 v[4:5], v[2:3], 0, s[14:15]
	s_add_i32 m0, s47, -16
	v_lshl_add_u64 v[0:1], v[0:1], 0, s[16:17]
	global_load_lds_dwordx4 v[4:5], off
	v_add_u32_e32 v4, 0x6000, v143
	s_and_b32 s28, s34, 0x700
	v_readfirstlane_b32 s47, v4
	s_add_i32 m0, s47, -16
	s_lshl_b32 s33, s33, 11
	global_load_lds_dwordx4 v[0:1], off
	v_lshl_add_u64 v[0:1], v[2:3], 0, s[16:17]
	v_add_u32_e32 v2, 0xe000, v143
	s_or_b32 s28, s28, s33
	v_readfirstlane_b32 s47, v2
	s_add_i32 m0, s47, -16
	v_mov_b32_e32 v2, v129
	global_load_lds_dwordx4 v[0:1], off
	v_add_u32_e32 v0, s28, v142
	s_lshl_b32 s28, s46, 14
	v_subrev_u32_e32 v0, s28, v0
	v_ashrrev_i32_e32 v1, 31, v0
	s_lshl_b32 s28, s46, 10
	v_lshlrev_b64 v[0:1], 12, v[0:1]
	s_or_b32 s28, s29, s28
	v_lshl_add_u64 v[138:139], v[134:135], 0, v[0:1]
	v_add_u32_e32 v0, s28, v142
	v_ashrrev_i32_e32 v1, 31, v0
	v_lshlrev_b64 v[0:1], 12, v[0:1]
	v_lshl_add_u64 v[140:141], v[136:137], 0, v[0:1]
	s_mov_b64 s[28:29], 0
	s_mov_b32 s46, 0
	v_mov_b32_e32 v0, 0
	v_mov_b32_e32 v1, v129
	v_mov_b32_e32 v3, v129
	v_mov_b32_e32 v4, v129
	v_mov_b32_e32 v5, v129
	v_mov_b32_e32 v6, v129
	v_mov_b32_e32 v7, v129
	v_mov_b32_e32 v8, v129
	v_mov_b32_e32 v9, v129
	v_mov_b32_e32 v10, v129
	v_mov_b32_e32 v11, v129
	v_mov_b32_e32 v12, v129
	v_mov_b32_e32 v13, v129
	v_mov_b32_e32 v14, v129
	v_mov_b32_e32 v15, v129
	v_mov_b32_e32 v16, 0
	v_mov_b32_e32 v17, v129
	v_mov_b32_e32 v18, v129
	v_mov_b32_e32 v19, v129
	v_mov_b32_e32 v20, v129
	v_mov_b32_e32 v21, v129
	v_mov_b32_e32 v22, v129
	v_mov_b32_e32 v23, v129
	v_mov_b32_e32 v24, v129
	v_mov_b32_e32 v25, v129
	v_mov_b32_e32 v26, v129
	v_mov_b32_e32 v27, v129
	v_mov_b32_e32 v28, v129
	v_mov_b32_e32 v29, v129
	v_mov_b32_e32 v30, v129
	v_mov_b32_e32 v31, v129
	v_mov_b32_e32 v32, 0
	v_mov_b32_e32 v33, v129
	v_mov_b32_e32 v34, v129
	v_mov_b32_e32 v35, v129
	v_mov_b32_e32 v36, v129
	v_mov_b32_e32 v37, v129
	v_mov_b32_e32 v38, v129
	v_mov_b32_e32 v39, v129
	v_mov_b32_e32 v40, v129
	v_mov_b32_e32 v41, v129
	v_mov_b32_e32 v42, v129
	v_mov_b32_e32 v43, v129
	v_mov_b32_e32 v44, v129
	v_mov_b32_e32 v45, v129
	v_mov_b32_e32 v46, v129
	v_mov_b32_e32 v47, v129
	v_mov_b32_e32 v48, 0
	v_mov_b32_e32 v49, v129
	v_mov_b32_e32 v50, v129
	v_mov_b32_e32 v51, v129
	v_mov_b32_e32 v52, v129
	v_mov_b32_e32 v53, v129
	v_mov_b32_e32 v54, v129
	v_mov_b32_e32 v55, v129
	v_mov_b32_e32 v56, v129
	v_mov_b32_e32 v57, v129
	v_mov_b32_e32 v58, v129
	v_mov_b32_e32 v59, v129
	v_mov_b32_e32 v60, v129
	v_mov_b32_e32 v61, v129
	v_mov_b32_e32 v62, v129
	v_mov_b32_e32 v63, v129
	v_mov_b32_e32 v64, 0
	v_mov_b32_e32 v65, v129
	v_mov_b32_e32 v66, v129
	v_mov_b32_e32 v67, v129
	v_mov_b32_e32 v68, v129
	v_mov_b32_e32 v69, v129
	v_mov_b32_e32 v70, v129
	v_mov_b32_e32 v71, v129
	v_mov_b32_e32 v72, v129
	v_mov_b32_e32 v73, v129
	v_mov_b32_e32 v74, v129
	v_mov_b32_e32 v75, v129
	v_mov_b32_e32 v76, v129
	v_mov_b32_e32 v77, v129
	v_mov_b32_e32 v78, v129
	v_mov_b32_e32 v79, v129
	v_mov_b32_e32 v80, 0
	v_mov_b32_e32 v81, v129
	v_mov_b32_e32 v82, v129
	v_mov_b32_e32 v83, v129
	v_mov_b32_e32 v84, v129
	v_mov_b32_e32 v85, v129
	v_mov_b32_e32 v86, v129
	v_mov_b32_e32 v87, v129
	v_mov_b32_e32 v88, v129
	v_mov_b32_e32 v89, v129
	v_mov_b32_e32 v90, v129
	v_mov_b32_e32 v91, v129
	v_mov_b32_e32 v92, v129
	v_mov_b32_e32 v93, v129
	v_mov_b32_e32 v94, v129
	v_mov_b32_e32 v95, v129
	v_mov_b32_e32 v96, 0
	v_mov_b32_e32 v97, v129
	v_mov_b32_e32 v98, v129
	v_mov_b32_e32 v99, v129
	v_mov_b32_e32 v100, v129
	v_mov_b32_e32 v101, v129
	v_mov_b32_e32 v102, v129
	v_mov_b32_e32 v103, v129
	v_mov_b32_e32 v104, v129
	v_mov_b32_e32 v105, v129
	v_mov_b32_e32 v106, v129
	v_mov_b32_e32 v107, v129
	v_mov_b32_e32 v108, v129
	v_mov_b32_e32 v109, v129
	v_mov_b32_e32 v110, v129
	v_mov_b32_e32 v111, v129
	v_mov_b32_e32 v112, 0
	v_mov_b32_e32 v113, v129
	v_mov_b32_e32 v114, v129
	v_mov_b32_e32 v115, v129
	v_mov_b32_e32 v116, v129
	v_mov_b32_e32 v117, v129
	v_mov_b32_e32 v118, v129
	v_mov_b32_e32 v119, v129
	v_mov_b32_e32 v120, v129
	v_mov_b32_e32 v121, v129
	v_mov_b32_e32 v122, v129
	v_mov_b32_e32 v123, v129
	v_mov_b32_e32 v124, v129
	v_mov_b32_e32 v125, v129
	v_mov_b32_e32 v126, v129
	v_mov_b32_e32 v127, v129
	s_waitcnt vmcnt(0) lgkmcnt(0)
	s_barrier
	v_readfirstlane_b32 s48, v143
	s_sub_u32 s48, s48, 16
	s_mov_b32 s49, 0
	s_mov_b32 s50, 0x8000
	s_mov_b32 s52, 0x10000
	v_and_b32_e32 v249, 63, v186
	v_and_b32_e32 v250, 15, v249
	v_lshrrev_b32_e32 v245, 4, v249
	v_bfe_u32 v246, v249, 1, 3
	v_xor_b32_e32 v240, v245, v246
	v_or_b32_e32 v245, 4, v245
	v_xor_b32_e32 v241, v245, v246
	v_lshlrev_b32_e32 v240, 4, v240
	v_lshlrev_b32_e32 v241, 4, v241
	v_lshl_add_u32 v240, v250, 7, v240
	v_lshl_add_u32 v241, v250, 7, v241
	v_bfe_u32 v245, v186, 6, 2
	v_lshl_add_u32 v243, v245, 13, v240
	v_lshl_add_u32 v244, v245, 13, v241
	v_lshrrev_b32_e32 v245, 8, v186
	v_lshl_add_u32 v240, v245, 14, v240
	v_lshl_add_u32 v241, v245, 14, v241
	v_readfirstlane_b32 s56, v138
	v_readfirstlane_b32 s57, v139
	s_and_b32 s53, s48, 0x400
	s_lshr_b32 s53, s53, 4
	s_sub_u32 s56, s56, s53
	s_subb_u32 s57, s57, 0
	v_subrev_u32_e32 v247, s56, v138
	s_add_u32 s62, s56, s24
	s_addc_u32 s63, s57, s25
	s_add_u32 s60, s56, s22
	s_addc_u32 s61, s57, s23
	s_add_u32 s58, s56, s20
	s_addc_u32 s59, s57, s21
	s_add_u32 s56, s56, s18
	s_addc_u32 s57, s57, s19
	v_readfirstlane_b32 s64, v140
	v_readfirstlane_b32 s65, v141
	s_and_b32 s53, s48, 0x400
	s_lshr_b32 s53, s53, 4
	s_sub_u32 s64, s64, s53
	s_subb_u32 s65, s65, 0
	v_subrev_u32_e32 v248, s64, v140
	s_add_u32 s70, s64, s24
	s_addc_u32 s71, s65, s25
	s_add_u32 s68, s64, s22
	s_addc_u32 s69, s65, s23
	s_add_u32 s66, s64, s20
	s_addc_u32 s67, s65, s21
	s_add_u32 s64, s64, s18
	s_addc_u32 s65, s65, s19
	s_add_u32 m0, s52, s48
	s_nop 0
	global_load_lds_dwordx4 v247, s[56:57]
	s_add_u32 s56, s56, 0x80
	s_addc_u32 s57, s57, 0
	s_add_u32 s53, s52, s48
	s_add_u32 m0, s53, 0x2000
	s_nop 0
	global_load_lds_dwordx4 v247, s[58:59]
	s_add_u32 s58, s58, 0x80
	s_addc_u32 s59, s59, 0
	s_add_u32 s53, s52, s48
	s_add_u32 m0, s53, 0x4000
	s_nop 0
	global_load_lds_dwordx4 v247, s[60:61]
	s_add_u32 s60, s60, 0x80
	s_addc_u32 s61, s61, 0
	s_add_u32 s53, s52, s48
	s_add_u32 m0, s53, 0x6000
	s_nop 0
	global_load_lds_dwordx4 v247, s[62:63]
	s_add_u32 s62, s62, 0x80
	s_addc_u32 s63, s63, 0
	v_add_u32_e32 v246, s50, v243
	v_add_u32_e32 v245, s49, v240
	ds_read_b128 v[192:195], v246
	ds_read_b128 v[196:199], v246 offset:2048
	ds_read_b128 v[200:203], v246 offset:4096
	ds_read_b128 v[204:207], v246 offset:6144
	ds_read_b128 v[224:227], v245
	ds_read_b128 v[228:231], v245 offset:2048
	ds_read_b128 v[232:235], v245 offset:4096
	ds_read_b128 v[236:239], v245 offset:6144
.Lg163_loop:
	s_add_u32 s51, s50, 0x10000
	s_sub_u32 s53, s51, 0x28000
	s_cmp_ge_u32 s51, 0x28000
	s_cselect_b32 s51, s53, s51
	s_add_u32 s52, s49, 0x20000
	s_sub_u32 s53, s52, 0x28000
	s_cmp_ge_u32 s52, 0x28000
	s_cselect_b32 s52, s53, s52
	v_add_u32_e32 v246, s50, v244
	s_waitcnt lgkmcnt(4)
	s_waitcnt lgkmcnt(3)
	v_mfma_f32_16x16x32_bf16 v[112:115], v[192:195], v[224:227], v[112:115]
	v_mfma_f32_16x16x32_bf16 v[120:123], v[196:199], v[224:227], v[120:123]
	v_mfma_f32_16x16x32_bf16 v[96:99], v[200:203], v[224:227], v[96:99]
	v_mfma_f32_16x16x32_bf16 v[104:107], v[204:207], v[224:227], v[104:107]
	s_add_u32 m0, s51, s48
	s_nop 0
	global_load_lds_dwordx4 v248, s[64:65]
	s_add_u32 s64, s64, 0x80
	s_addc_u32 s65, s65, 0
	ds_read_b128 v[224:227], v245 offset:8192
	ds_read_b128 v[208:211], v246
	s_waitcnt lgkmcnt(4)
	v_mfma_f32_16x16x32_bf16 v[116:119], v[192:195], v[228:231], v[116:119]
	v_mfma_f32_16x16x32_bf16 v[124:127], v[196:199], v[228:231], v[124:127]
	v_mfma_f32_16x16x32_bf16 v[100:103], v[200:203], v[228:231], v[100:103]
	v_mfma_f32_16x16x32_bf16 v[108:111], v[204:207], v[228:231], v[108:111]
	s_add_u32 s53, s51, s48
	s_add_u32 m0, s53, 0x2000
	s_nop 0
	global_load_lds_dwordx4 v248, s[66:67]
	s_add_u32 s66, s66, 0x80
	s_addc_u32 s67, s67, 0
	ds_read_b128 v[228:231], v245 offset:10240
	ds_read_b128 v[212:215], v246 offset:2048
	s_waitcnt lgkmcnt(5)
	v_mfma_f32_16x16x32_bf16 v[80:83], v[192:195], v[232:235], v[80:83]
	v_mfma_f32_16x16x32_bf16 v[88:91], v[196:199], v[232:235], v[88:91]
	v_mfma_f32_16x16x32_bf16 v[64:67], v[200:203], v[232:235], v[64:67]
	v_mfma_f32_16x16x32_bf16 v[72:75], v[204:207], v[232:235], v[72:75]
	s_add_u32 s53, s51, s48
	s_add_u32 m0, s53, 0x4000
	s_nop 0
	global_load_lds_dwordx4 v248, s[68:69]
	s_add_u32 s68, s68, 0x80
	s_addc_u32 s69, s69, 0
	ds_read_b128 v[232:235], v245 offset:12288
	ds_read_b128 v[216:219], v246 offset:4096
	s_waitcnt lgkmcnt(6)
	v_mfma_f32_16x16x32_bf16 v[84:87], v[192:195], v[236:239], v[84:87]
	v_mfma_f32_16x16x32_bf16 v[92:95], v[196:199], v[236:239], v[92:95]
	v_mfma_f32_16x16x32_bf16 v[68:71], v[200:203], v[236:239], v[68:71]
	v_mfma_f32_16x16x32_bf16 v[76:79], v[204:207], v[236:239], v[76:79]
	s_add_u32 s53, s51, s48
	s_add_u32 m0, s53, 0x6000
	s_nop 0
	global_load_lds_dwordx4 v248, s[70:71]
	s_add_u32 s70, s70, 0x80
	s_addc_u32 s71, s71, 0
	ds_read_b128 v[236:239], v245 offset:14336
	ds_read_b128 v[220:223], v246 offset:6144
	v_add_u32_e32 v245, s49, v241
	s_waitcnt lgkmcnt(7)
	v_mfma_f32_16x16x32_bf16 v[48:51], v[192:195], v[224:227], v[48:51]
	v_mfma_f32_16x16x32_bf16 v[56:59], v[196:199], v[224:227], v[56:59]
	v_mfma_f32_16x16x32_bf16 v[32:35], v[200:203], v[224:227], v[32:35]
	v_mfma_f32_16x16x32_bf16 v[40:43], v[204:207], v[224:227], v[40:43]
	s_add_u32 m0, s52, s48
	s_nop 0
	global_load_lds_dwordx4 v247, s[56:57]
	s_add_u32 s56, s56, 0x80
	s_addc_u32 s57, s57, 0
	ds_read_b128 v[224:227], v245
	s_waitcnt lgkmcnt(6)
	v_mfma_f32_16x16x32_bf16 v[52:55], v[192:195], v[228:231], v[52:55]
	v_mfma_f32_16x16x32_bf16 v[60:63], v[196:199], v[228:231], v[60:63]
	v_mfma_f32_16x16x32_bf16 v[36:39], v[200:203], v[228:231], v[36:39]
	v_mfma_f32_16x16x32_bf16 v[44:47], v[204:207], v[228:231], v[44:47]
	s_add_u32 s53, s52, s48
	s_add_u32 m0, s53, 0x2000
	s_nop 0
	global_load_lds_dwordx4 v247, s[58:59]
	s_add_u32 s58, s58, 0x80
	s_addc_u32 s59, s59, 0
	ds_read_b128 v[228:231], v245 offset:2048
	s_waitcnt lgkmcnt(5)
	v_mfma_f32_16x16x32_bf16 v[16:19], v[192:195], v[232:235], v[16:19]
	v_mfma_f32_16x16x32_bf16 v[24:27], v[196:199], v[232:235], v[24:27]
	v_mfma_f32_16x16x32_bf16 v[0:3], v[200:203], v[232:235], v[0:3]
	v_mfma_f32_16x16x32_bf16 v[8:11], v[204:207], v[232:235], v[8:11]
	s_add_u32 s53, s52, s48
	s_add_u32 m0, s53, 0x4000
	s_nop 0
	global_load_lds_dwordx4 v247, s[60:61]
	s_add_u32 s60, s60, 0x80
	s_addc_u32 s61, s61, 0
	ds_read_b128 v[232:235], v245 offset:4096
	s_waitcnt lgkmcnt(4)
	v_mfma_f32_16x16x32_bf16 v[20:23], v[192:195], v[236:239], v[20:23]
	v_mfma_f32_16x16x32_bf16 v[28:31], v[196:199], v[236:239], v[28:31]
	v_mfma_f32_16x16x32_bf16 v[4:7], v[200:203], v[236:239], v[4:7]
	v_mfma_f32_16x16x32_bf16 v[12:15], v[204:207], v[236:239], v[12:15]
	s_add_u32 s53, s52, s48
	s_add_u32 m0, s53, 0x6000
	s_nop 0
	global_load_lds_dwordx4 v247, s[62:63]
	s_add_u32 s62, s62, 0x80
	s_addc_u32 s63, s63, 0
	ds_read_b128 v[236:239], v245 offset:6144
	s_waitcnt lgkmcnt(4)
	s_waitcnt lgkmcnt(3)
	v_mfma_f32_16x16x32_bf16 v[112:115], v[208:211], v[224:227], v[112:115]
	v_mfma_f32_16x16x32_bf16 v[120:123], v[212:215], v[224:227], v[120:123]
	v_mfma_f32_16x16x32_bf16 v[96:99], v[216:219], v[224:227], v[96:99]
	v_mfma_f32_16x16x32_bf16 v[104:107], v[220:223], v[224:227], v[104:107]
	ds_read_b128 v[224:227], v245 offset:8192
	s_waitcnt lgkmcnt(3)
	v_mfma_f32_16x16x32_bf16 v[116:119], v[208:211], v[228:231], v[116:119]
	v_mfma_f32_16x16x32_bf16 v[124:127], v[212:215], v[228:231], v[124:127]
	v_mfma_f32_16x16x32_bf16 v[100:103], v[216:219], v[228:231], v[100:103]
	v_mfma_f32_16x16x32_bf16 v[108:111], v[220:223], v[228:231], v[108:111]
	ds_read_b128 v[228:231], v245 offset:10240
	s_waitcnt lgkmcnt(3)
	v_mfma_f32_16x16x32_bf16 v[80:83], v[208:211], v[232:235], v[80:83]
	v_mfma_f32_16x16x32_bf16 v[88:91], v[212:215], v[232:235], v[88:91]
	v_mfma_f32_16x16x32_bf16 v[64:67], v[216:219], v[232:235], v[64:67]
	v_mfma_f32_16x16x32_bf16 v[72:75], v[220:223], v[232:235], v[72:75]
	ds_read_b128 v[232:235], v245 offset:12288
	s_waitcnt lgkmcnt(3)
	v_mfma_f32_16x16x32_bf16 v[84:87], v[208:211], v[236:239], v[84:87]
	v_mfma_f32_16x16x32_bf16 v[92:95], v[212:215], v[236:239], v[92:95]
	v_mfma_f32_16x16x32_bf16 v[68:71], v[216:219], v[236:239], v[68:71]
	v_mfma_f32_16x16x32_bf16 v[76:79], v[220:223], v[236:239], v[76:79]
	ds_read_b128 v[236:239], v245 offset:14336
	s_waitcnt lgkmcnt(3)
	v_mfma_f32_16x16x32_bf16 v[48:51], v[208:211], v[224:227], v[48:51]
	v_mfma_f32_16x16x32_bf16 v[56:59], v[212:215], v[224:227], v[56:59]
	v_mfma_f32_16x16x32_bf16 v[32:35], v[216:219], v[224:227], v[32:35]
	v_mfma_f32_16x16x32_bf16 v[40:43], v[220:223], v[224:227], v[40:43]
	s_waitcnt lgkmcnt(2)
	v_mfma_f32_16x16x32_bf16 v[52:55], v[208:211], v[228:231], v[52:55]
	v_mfma_f32_16x16x32_bf16 v[60:63], v[212:215], v[228:231], v[60:63]
	v_mfma_f32_16x16x32_bf16 v[36:39], v[216:219], v[228:231], v[36:39]
	v_mfma_f32_16x16x32_bf16 v[44:47], v[220:223], v[228:231], v[44:47]
	s_waitcnt lgkmcnt(0)
	s_add_u32 s28, s28, 0x80
	s_addc_u32 s29, s29, 0
	s_add_u32 s49, s49, 0x10000
	s_sub_u32 s53, s49, 0x28000
	s_cmp_ge_u32 s49, 0x28000
	s_cselect_b32 s49, s53, s49
	s_mov_b32 s50, s51
	s_waitcnt vmcnt(4)
	s_barrier
	v_add_u32_e32 v246, s50, v243
	v_add_u32_e32 v245, s49, v240
	ds_read_b128 v[192:195], v246
	ds_read_b128 v[196:199], v246 offset:2048
	ds_read_b128 v[200:203], v246 offset:4096
	ds_read_b128 v[204:207], v246 offset:6144
	ds_read_b128 v[224:227], v245
	ds_read_b128 v[228:231], v245 offset:2048
	v_mfma_f32_16x16x32_bf16 v[16:19], v[208:211], v[232:235], v[16:19]
	v_mfma_f32_16x16x32_bf16 v[24:27], v[212:215], v[232:235], v[24:27]
	v_mfma_f32_16x16x32_bf16 v[0:3], v[216:219], v[232:235], v[0:3]
	v_mfma_f32_16x16x32_bf16 v[8:11], v[220:223], v[232:235], v[8:11]
	ds_read_b128 v[232:235], v245 offset:4096
	v_mfma_f32_16x16x32_bf16 v[20:23], v[208:211], v[236:239], v[20:23]
	v_mfma_f32_16x16x32_bf16 v[28:31], v[212:215], v[236:239], v[28:31]
	v_mfma_f32_16x16x32_bf16 v[4:7], v[216:219], v[236:239], v[4:7]
	v_mfma_f32_16x16x32_bf16 v[12:15], v[220:223], v[236:239], v[12:15]
	ds_read_b128 v[236:239], v245 offset:6144
	s_cmpk_lg_i32 s28, 0xf00
	s_cbranch_scc1 .Lg163_loop
	s_add_u32 s51, s50, 0x10000
	s_sub_u32 s53, s51, 0x28000
	s_cmp_ge_u32 s51, 0x28000
	s_cselect_b32 s51, s53, s51
	v_add_u32_e32 v246, s50, v244
	s_waitcnt lgkmcnt(4)
	s_waitcnt lgkmcnt(3)
	v_mfma_f32_16x16x32_bf16 v[112:115], v[192:195], v[224:227], v[112:115]
	v_mfma_f32_16x16x32_bf16 v[120:123], v[196:199], v[224:227], v[120:123]
	v_mfma_f32_16x16x32_bf16 v[96:99], v[200:203], v[224:227], v[96:99]
	v_mfma_f32_16x16x32_bf16 v[104:107], v[204:207], v[224:227], v[104:107]
	s_add_u32 m0, s51, s48
	s_nop 0
	global_load_lds_dwordx4 v248, s[64:65]
	s_add_u32 s64, s64, 0x80
	s_addc_u32 s65, s65, 0
	ds_read_b128 v[224:227], v245 offset:8192
	ds_read_b128 v[208:211], v246
	s_waitcnt lgkmcnt(4)
	v_mfma_f32_16x16x32_bf16 v[116:119], v[192:195], v[228:231], v[116:119]
	v_mfma_f32_16x16x32_bf16 v[124:127], v[196:199], v[228:231], v[124:127]
	v_mfma_f32_16x16x32_bf16 v[100:103], v[200:203], v[228:231], v[100:103]
	v_mfma_f32_16x16x32_bf16 v[108:111], v[204:207], v[228:231], v[108:111]
	s_add_u32 s53, s51, s48
	s_add_u32 m0, s53, 0x2000
	s_nop 0
	global_load_lds_dwordx4 v248, s[66:67]
	s_add_u32 s66, s66, 0x80
	s_addc_u32 s67, s67, 0
	ds_read_b128 v[228:231], v245 offset:10240
	ds_read_b128 v[212:215], v246 offset:2048
	s_waitcnt lgkmcnt(5)
	v_mfma_f32_16x16x32_bf16 v[80:83], v[192:195], v[232:235], v[80:83]
	v_mfma_f32_16x16x32_bf16 v[88:91], v[196:199], v[232:235], v[88:91]
	v_mfma_f32_16x16x32_bf16 v[64:67], v[200:203], v[232:235], v[64:67]
	v_mfma_f32_16x16x32_bf16 v[72:75], v[204:207], v[232:235], v[72:75]
	s_add_u32 s53, s51, s48
	s_add_u32 m0, s53, 0x4000
	s_nop 0
	global_load_lds_dwordx4 v248, s[68:69]
	s_add_u32 s68, s68, 0x80
	s_addc_u32 s69, s69, 0
	ds_read_b128 v[232:235], v245 offset:12288
	ds_read_b128 v[216:219], v246 offset:4096
	s_waitcnt lgkmcnt(6)
	v_mfma_f32_16x16x32_bf16 v[84:87], v[192:195], v[236:239], v[84:87]
	v_mfma_f32_16x16x32_bf16 v[92:95], v[196:199], v[236:239], v[92:95]
	v_mfma_f32_16x16x32_bf16 v[68:71], v[200:203], v[236:239], v[68:71]
	v_mfma_f32_16x16x32_bf16 v[76:79], v[204:207], v[236:239], v[76:79]
	s_add_u32 s53, s51, s48
	s_add_u32 m0, s53, 0x6000
	s_nop 0
	global_load_lds_dwordx4 v248, s[70:71]
	s_add_u32 s70, s70, 0x80
	s_addc_u32 s71, s71, 0
	ds_read_b128 v[236:239], v245 offset:14336
	ds_read_b128 v[220:223], v246 offset:6144
	v_add_u32_e32 v245, s49, v241
	s_waitcnt lgkmcnt(7)
	v_mfma_f32_16x16x32_bf16 v[48:51], v[192:195], v[224:227], v[48:51]
	v_mfma_f32_16x16x32_bf16 v[56:59], v[196:199], v[224:227], v[56:59]
	v_mfma_f32_16x16x32_bf16 v[32:35], v[200:203], v[224:227], v[32:35]
	v_mfma_f32_16x16x32_bf16 v[40:43], v[204:207], v[224:227], v[40:43]
	ds_read_b128 v[224:227], v245
	s_waitcnt lgkmcnt(6)
	v_mfma_f32_16x16x32_bf16 v[52:55], v[192:195], v[228:231], v[52:55]
	v_mfma_f32_16x16x32_bf16 v[60:63], v[196:199], v[228:231], v[60:63]
	v_mfma_f32_16x16x32_bf16 v[36:39], v[200:203], v[228:231], v[36:39]
	v_mfma_f32_16x16x32_bf16 v[44:47], v[204:207], v[228:231], v[44:47]
	ds_read_b128 v[228:231], v245 offset:2048
	s_waitcnt lgkmcnt(5)
	v_mfma_f32_16x16x32_bf16 v[16:19], v[192:195], v[232:235], v[16:19]
	v_mfma_f32_16x16x32_bf16 v[24:27], v[196:199], v[232:235], v[24:27]
	v_mfma_f32_16x16x32_bf16 v[0:3], v[200:203], v[232:235], v[0:3]
	v_mfma_f32_16x16x32_bf16 v[8:11], v[204:207], v[232:235], v[8:11]
	ds_read_b128 v[232:235], v245 offset:4096
	s_waitcnt lgkmcnt(4)
	v_mfma_f32_16x16x32_bf16 v[20:23], v[192:195], v[236:239], v[20:23]
	v_mfma_f32_16x16x32_bf16 v[28:31], v[196:199], v[236:239], v[28:31]
	v_mfma_f32_16x16x32_bf16 v[4:7], v[200:203], v[236:239], v[4:7]
	v_mfma_f32_16x16x32_bf16 v[12:15], v[204:207], v[236:239], v[12:15]
	ds_read_b128 v[236:239], v245 offset:6144
	s_waitcnt lgkmcnt(4)
	s_waitcnt lgkmcnt(3)
	v_mfma_f32_16x16x32_bf16 v[112:115], v[208:211], v[224:227], v[112:115]
	v_mfma_f32_16x16x32_bf16 v[120:123], v[212:215], v[224:227], v[120:123]
	v_mfma_f32_16x16x32_bf16 v[96:99], v[216:219], v[224:227], v[96:99]
	v_mfma_f32_16x16x32_bf16 v[104:107], v[220:223], v[224:227], v[104:107]
	ds_read_b128 v[224:227], v245 offset:8192
	s_waitcnt lgkmcnt(3)
	v_mfma_f32_16x16x32_bf16 v[116:119], v[208:211], v[228:231], v[116:119]
	v_mfma_f32_16x16x32_bf16 v[124:127], v[212:215], v[228:231], v[124:127]
	v_mfma_f32_16x16x32_bf16 v[100:103], v[216:219], v[228:231], v[100:103]
	v_mfma_f32_16x16x32_bf16 v[108:111], v[220:223], v[228:231], v[108:111]
	ds_read_b128 v[228:231], v245 offset:10240
	s_waitcnt lgkmcnt(3)
	v_mfma_f32_16x16x32_bf16 v[80:83], v[208:211], v[232:235], v[80:83]
	v_mfma_f32_16x16x32_bf16 v[88:91], v[212:215], v[232:235], v[88:91]
	v_mfma_f32_16x16x32_bf16 v[64:67], v[216:219], v[232:235], v[64:67]
	v_mfma_f32_16x16x32_bf16 v[72:75], v[220:223], v[232:235], v[72:75]
	ds_read_b128 v[232:235], v245 offset:12288
	s_waitcnt lgkmcnt(3)
	v_mfma_f32_16x16x32_bf16 v[84:87], v[208:211], v[236:239], v[84:87]
	v_mfma_f32_16x16x32_bf16 v[92:95], v[212:215], v[236:239], v[92:95]
	v_mfma_f32_16x16x32_bf16 v[68:71], v[216:219], v[236:239], v[68:71]
	v_mfma_f32_16x16x32_bf16 v[76:79], v[220:223], v[236:239], v[76:79]
	ds_read_b128 v[236:239], v245 offset:14336
	s_waitcnt lgkmcnt(3)
	v_mfma_f32_16x16x32_bf16 v[48:51], v[208:211], v[224:227], v[48:51]
	v_mfma_f32_16x16x32_bf16 v[56:59], v[212:215], v[224:227], v[56:59]
	v_mfma_f32_16x16x32_bf16 v[32:35], v[216:219], v[224:227], v[32:35]
	v_mfma_f32_16x16x32_bf16 v[40:43], v[220:223], v[224:227], v[40:43]
	s_waitcnt lgkmcnt(2)
	v_mfma_f32_16x16x32_bf16 v[52:55], v[208:211], v[228:231], v[52:55]
	v_mfma_f32_16x16x32_bf16 v[60:63], v[212:215], v[228:231], v[60:63]
	v_mfma_f32_16x16x32_bf16 v[36:39], v[216:219], v[228:231], v[36:39]
	v_mfma_f32_16x16x32_bf16 v[44:47], v[220:223], v[228:231], v[44:47]
	s_waitcnt lgkmcnt(0)
	s_add_u32 s28, s28, 0x80
	s_addc_u32 s29, s29, 0
	s_add_u32 s49, s49, 0x10000
	s_sub_u32 s53, s49, 0x28000
	s_cmp_ge_u32 s49, 0x28000
	s_cselect_b32 s49, s53, s49
	s_mov_b32 s50, s51
	s_waitcnt vmcnt(0)
	s_barrier
	v_add_u32_e32 v246, s50, v243
	v_add_u32_e32 v245, s49, v240
	ds_read_b128 v[192:195], v246
	ds_read_b128 v[196:199], v246 offset:2048
	ds_read_b128 v[200:203], v246 offset:4096
	ds_read_b128 v[204:207], v246 offset:6144
	ds_read_b128 v[224:227], v245
	ds_read_b128 v[228:231], v245 offset:2048
	v_mfma_f32_16x16x32_bf16 v[16:19], v[208:211], v[232:235], v[16:19]
	v_mfma_f32_16x16x32_bf16 v[24:27], v[212:215], v[232:235], v[24:27]
	v_mfma_f32_16x16x32_bf16 v[0:3], v[216:219], v[232:235], v[0:3]
	v_mfma_f32_16x16x32_bf16 v[8:11], v[220:223], v[232:235], v[8:11]
	ds_read_b128 v[232:235], v245 offset:4096
	v_mfma_f32_16x16x32_bf16 v[20:23], v[208:211], v[236:239], v[20:23]
	v_mfma_f32_16x16x32_bf16 v[28:31], v[212:215], v[236:239], v[28:31]
	v_mfma_f32_16x16x32_bf16 v[4:7], v[216:219], v[236:239], v[4:7]
	v_mfma_f32_16x16x32_bf16 v[12:15], v[220:223], v[236:239], v[12:15]
	ds_read_b128 v[236:239], v245 offset:6144
	v_add_u32_e32 v246, s50, v244
	s_waitcnt lgkmcnt(4)
	s_waitcnt lgkmcnt(3)
	v_mfma_f32_16x16x32_bf16 v[112:115], v[192:195], v[224:227], v[112:115]
	v_mfma_f32_16x16x32_bf16 v[120:123], v[196:199], v[224:227], v[120:123]
	v_mfma_f32_16x16x32_bf16 v[96:99], v[200:203], v[224:227], v[96:99]
	v_mfma_f32_16x16x32_bf16 v[104:107], v[204:207], v[224:227], v[104:107]
	ds_read_b128 v[224:227], v245 offset:8192
	ds_read_b128 v[208:211], v246
	s_waitcnt lgkmcnt(4)
	v_mfma_f32_16x16x32_bf16 v[116:119], v[192:195], v[228:231], v[116:119]
	v_mfma_f32_16x16x32_bf16 v[124:127], v[196:199], v[228:231], v[124:127]
	v_mfma_f32_16x16x32_bf16 v[100:103], v[200:203], v[228:231], v[100:103]
	v_mfma_f32_16x16x32_bf16 v[108:111], v[204:207], v[228:231], v[108:111]
	ds_read_b128 v[228:231], v245 offset:10240
	ds_read_b128 v[212:215], v246 offset:2048
	s_waitcnt lgkmcnt(5)
	v_mfma_f32_16x16x32_bf16 v[80:83], v[192:195], v[232:235], v[80:83]
	v_mfma_f32_16x16x32_bf16 v[88:91], v[196:199], v[232:235], v[88:91]
	v_mfma_f32_16x16x32_bf16 v[64:67], v[200:203], v[232:235], v[64:67]
	v_mfma_f32_16x16x32_bf16 v[72:75], v[204:207], v[232:235], v[72:75]
	ds_read_b128 v[232:235], v245 offset:12288
	ds_read_b128 v[216:219], v246 offset:4096
	s_waitcnt lgkmcnt(6)
	v_mfma_f32_16x16x32_bf16 v[84:87], v[192:195], v[236:239], v[84:87]
	v_mfma_f32_16x16x32_bf16 v[92:95], v[196:199], v[236:239], v[92:95]
	v_mfma_f32_16x16x32_bf16 v[68:71], v[200:203], v[236:239], v[68:71]
	v_mfma_f32_16x16x32_bf16 v[76:79], v[204:207], v[236:239], v[76:79]
	ds_read_b128 v[236:239], v245 offset:14336
	ds_read_b128 v[220:223], v246 offset:6144
	v_add_u32_e32 v245, s49, v241
	s_waitcnt lgkmcnt(7)
	v_mfma_f32_16x16x32_bf16 v[48:51], v[192:195], v[224:227], v[48:51]
	v_mfma_f32_16x16x32_bf16 v[56:59], v[196:199], v[224:227], v[56:59]
	v_mfma_f32_16x16x32_bf16 v[32:35], v[200:203], v[224:227], v[32:35]
	v_mfma_f32_16x16x32_bf16 v[40:43], v[204:207], v[224:227], v[40:43]
	ds_read_b128 v[224:227], v245
	s_waitcnt lgkmcnt(6)
	v_mfma_f32_16x16x32_bf16 v[52:55], v[192:195], v[228:231], v[52:55]
	v_mfma_f32_16x16x32_bf16 v[60:63], v[196:199], v[228:231], v[60:63]
	v_mfma_f32_16x16x32_bf16 v[36:39], v[200:203], v[228:231], v[36:39]
	v_mfma_f32_16x16x32_bf16 v[44:47], v[204:207], v[228:231], v[44:47]
	ds_read_b128 v[228:231], v245 offset:2048
	s_waitcnt lgkmcnt(5)
	v_mfma_f32_16x16x32_bf16 v[16:19], v[192:195], v[232:235], v[16:19]
	v_mfma_f32_16x16x32_bf16 v[24:27], v[196:199], v[232:235], v[24:27]
	v_mfma_f32_16x16x32_bf16 v[0:3], v[200:203], v[232:235], v[0:3]
	v_mfma_f32_16x16x32_bf16 v[8:11], v[204:207], v[232:235], v[8:11]
	ds_read_b128 v[232:235], v245 offset:4096
	s_waitcnt lgkmcnt(4)
	v_mfma_f32_16x16x32_bf16 v[20:23], v[192:195], v[236:239], v[20:23]
	v_mfma_f32_16x16x32_bf16 v[28:31], v[196:199], v[236:239], v[28:31]
	v_mfma_f32_16x16x32_bf16 v[4:7], v[200:203], v[236:239], v[4:7]
	v_mfma_f32_16x16x32_bf16 v[12:15], v[204:207], v[236:239], v[12:15]
	ds_read_b128 v[236:239], v245 offset:6144
	s_waitcnt lgkmcnt(4)
	s_waitcnt lgkmcnt(3)
	v_mfma_f32_16x16x32_bf16 v[112:115], v[208:211], v[224:227], v[112:115]
	v_mfma_f32_16x16x32_bf16 v[120:123], v[212:215], v[224:227], v[120:123]
	v_mfma_f32_16x16x32_bf16 v[96:99], v[216:219], v[224:227], v[96:99]
	v_mfma_f32_16x16x32_bf16 v[104:107], v[220:223], v[224:227], v[104:107]
	ds_read_b128 v[224:227], v245 offset:8192
	s_waitcnt lgkmcnt(3)
	v_mfma_f32_16x16x32_bf16 v[116:119], v[208:211], v[228:231], v[116:119]
	v_mfma_f32_16x16x32_bf16 v[124:127], v[212:215], v[228:231], v[124:127]
	v_mfma_f32_16x16x32_bf16 v[100:103], v[216:219], v[228:231], v[100:103]
	v_mfma_f32_16x16x32_bf16 v[108:111], v[220:223], v[228:231], v[108:111]
	ds_read_b128 v[228:231], v245 offset:10240
	s_waitcnt lgkmcnt(3)
	v_mfma_f32_16x16x32_bf16 v[80:83], v[208:211], v[232:235], v[80:83]
	v_mfma_f32_16x16x32_bf16 v[88:91], v[212:215], v[232:235], v[88:91]
	v_mfma_f32_16x16x32_bf16 v[64:67], v[216:219], v[232:235], v[64:67]
	v_mfma_f32_16x16x32_bf16 v[72:75], v[220:223], v[232:235], v[72:75]
	ds_read_b128 v[232:235], v245 offset:12288
	s_waitcnt lgkmcnt(3)
	v_mfma_f32_16x16x32_bf16 v[84:87], v[208:211], v[236:239], v[84:87]
	v_mfma_f32_16x16x32_bf16 v[92:95], v[212:215], v[236:239], v[92:95]
	v_mfma_f32_16x16x32_bf16 v[68:71], v[216:219], v[236:239], v[68:71]
	v_mfma_f32_16x16x32_bf16 v[76:79], v[220:223], v[236:239], v[76:79]
	ds_read_b128 v[236:239], v245 offset:14336
	s_waitcnt lgkmcnt(3)
	v_mfma_f32_16x16x32_bf16 v[48:51], v[208:211], v[224:227], v[48:51]
	v_mfma_f32_16x16x32_bf16 v[56:59], v[212:215], v[224:227], v[56:59]
	v_mfma_f32_16x16x32_bf16 v[32:35], v[216:219], v[224:227], v[32:35]
	v_mfma_f32_16x16x32_bf16 v[40:43], v[220:223], v[224:227], v[40:43]
	s_waitcnt lgkmcnt(2)
	v_mfma_f32_16x16x32_bf16 v[52:55], v[208:211], v[228:231], v[52:55]
	v_mfma_f32_16x16x32_bf16 v[60:63], v[212:215], v[228:231], v[60:63]
	v_mfma_f32_16x16x32_bf16 v[36:39], v[216:219], v[228:231], v[36:39]
	v_mfma_f32_16x16x32_bf16 v[44:47], v[220:223], v[228:231], v[44:47]
	s_waitcnt lgkmcnt(0)
	s_waitcnt vmcnt(0)
	s_barrier
	v_mfma_f32_16x16x32_bf16 v[16:19], v[208:211], v[232:235], v[16:19]
	v_mfma_f32_16x16x32_bf16 v[24:27], v[212:215], v[232:235], v[24:27]
	v_mfma_f32_16x16x32_bf16 v[0:3], v[216:219], v[232:235], v[0:3]
	v_mfma_f32_16x16x32_bf16 v[8:11], v[220:223], v[232:235], v[8:11]
	v_mfma_f32_16x16x32_bf16 v[20:23], v[208:211], v[236:239], v[20:23]
	v_mfma_f32_16x16x32_bf16 v[28:31], v[212:215], v[236:239], v[28:31]
	v_mfma_f32_16x16x32_bf16 v[4:7], v[216:219], v[236:239], v[4:7]
	v_mfma_f32_16x16x32_bf16 v[12:15], v[220:223], v[236:239], v[12:15]
	s_nop 15
	v_permlane16_swap_b32_e32 v112, v116
	v_permlane16_swap_b32_e32 v113, v117
	v_permlane16_swap_b32_e32 v114, v118
	v_permlane16_swap_b32_e32 v115, v119
	v_permlane16_swap_b32_e32 v120, v124
	v_permlane16_swap_b32_e32 v121, v125
	v_permlane16_swap_b32_e32 v122, v126
	v_permlane16_swap_b32_e32 v123, v127
	v_permlane16_swap_b32_e32 v96, v100
	v_permlane16_swap_b32_e32 v97, v101
	v_permlane16_swap_b32_e32 v98, v102
	v_permlane16_swap_b32_e32 v99, v103
	v_permlane16_swap_b32_e32 v104, v108
	v_permlane16_swap_b32_e32 v105, v109
	v_permlane16_swap_b32_e32 v106, v110
	v_permlane16_swap_b32_e32 v107, v111
	v_permlane16_swap_b32_e32 v80, v84
	v_permlane16_swap_b32_e32 v81, v85
	v_permlane16_swap_b32_e32 v82, v86
	v_permlane16_swap_b32_e32 v83, v87
	v_permlane16_swap_b32_e32 v88, v92
	v_permlane16_swap_b32_e32 v89, v93
	v_permlane16_swap_b32_e32 v90, v94
	v_permlane16_swap_b32_e32 v91, v95
	v_permlane16_swap_b32_e32 v64, v68
	v_permlane16_swap_b32_e32 v65, v69
	v_permlane16_swap_b32_e32 v66, v70
	v_permlane16_swap_b32_e32 v67, v71
	v_permlane16_swap_b32_e32 v72, v76
	v_permlane16_swap_b32_e32 v73, v77
	v_permlane16_swap_b32_e32 v74, v78
	v_permlane16_swap_b32_e32 v75, v79
	v_permlane16_swap_b32_e32 v48, v52
	v_permlane16_swap_b32_e32 v49, v53
	v_permlane16_swap_b32_e32 v50, v54
	v_permlane16_swap_b32_e32 v51, v55
	v_permlane16_swap_b32_e32 v56, v60
	v_permlane16_swap_b32_e32 v57, v61
	v_permlane16_swap_b32_e32 v58, v62
	v_permlane16_swap_b32_e32 v59, v63
	v_permlane16_swap_b32_e32 v32, v36
	v_permlane16_swap_b32_e32 v33, v37
	v_permlane16_swap_b32_e32 v34, v38
	v_permlane16_swap_b32_e32 v35, v39
	v_permlane16_swap_b32_e32 v40, v44
	v_permlane16_swap_b32_e32 v41, v45
	v_permlane16_swap_b32_e32 v42, v46
	v_permlane16_swap_b32_e32 v43, v47
	v_permlane16_swap_b32_e32 v16, v20
	v_permlane16_swap_b32_e32 v17, v21
	v_permlane16_swap_b32_e32 v18, v22
	v_permlane16_swap_b32_e32 v19, v23
	v_permlane16_swap_b32_e32 v24, v28
	v_permlane16_swap_b32_e32 v25, v29
	v_permlane16_swap_b32_e32 v26, v30
	v_permlane16_swap_b32_e32 v27, v31
	v_permlane16_swap_b32_e32 v0, v4
	v_permlane16_swap_b32_e32 v1, v5
	v_permlane16_swap_b32_e32 v2, v6
	v_permlane16_swap_b32_e32 v3, v7
	v_permlane16_swap_b32_e32 v8, v12
	v_permlane16_swap_b32_e32 v9, v13
	v_permlane16_swap_b32_e32 v10, v14
	v_permlane16_swap_b32_e32 v11, v15
	v_permlane32_swap_b32_e32 v112, v116
	v_permlane32_swap_b32_e32 v113, v117
	v_permlane32_swap_b32_e32 v114, v118
	v_permlane32_swap_b32_e32 v115, v119
	v_permlane32_swap_b32_e32 v120, v124
	v_permlane32_swap_b32_e32 v121, v125
	v_permlane32_swap_b32_e32 v122, v126
	v_permlane32_swap_b32_e32 v123, v127
	v_permlane32_swap_b32_e32 v96, v100
	v_permlane32_swap_b32_e32 v97, v101
	v_permlane32_swap_b32_e32 v98, v102
	v_permlane32_swap_b32_e32 v99, v103
	v_permlane32_swap_b32_e32 v104, v108
	v_permlane32_swap_b32_e32 v105, v109
	v_permlane32_swap_b32_e32 v106, v110
	v_permlane32_swap_b32_e32 v107, v111
	v_permlane32_swap_b32_e32 v80, v84
	v_permlane32_swap_b32_e32 v81, v85
	v_permlane32_swap_b32_e32 v82, v86
	v_permlane32_swap_b32_e32 v83, v87
	v_permlane32_swap_b32_e32 v88, v92
	v_permlane32_swap_b32_e32 v89, v93
	v_permlane32_swap_b32_e32 v90, v94
	v_permlane32_swap_b32_e32 v91, v95
	v_permlane32_swap_b32_e32 v64, v68
	v_permlane32_swap_b32_e32 v65, v69
	v_permlane32_swap_b32_e32 v66, v70
	v_permlane32_swap_b32_e32 v67, v71
	v_permlane32_swap_b32_e32 v72, v76
	v_permlane32_swap_b32_e32 v73, v77
	v_permlane32_swap_b32_e32 v74, v78
	v_permlane32_swap_b32_e32 v75, v79
	v_permlane32_swap_b32_e32 v48, v52
	v_permlane32_swap_b32_e32 v49, v53
	v_permlane32_swap_b32_e32 v50, v54
	v_permlane32_swap_b32_e32 v51, v55
	v_permlane32_swap_b32_e32 v56, v60
	v_permlane32_swap_b32_e32 v57, v61
	v_permlane32_swap_b32_e32 v58, v62
	v_permlane32_swap_b32_e32 v59, v63
	v_permlane32_swap_b32_e32 v32, v36
	v_permlane32_swap_b32_e32 v33, v37
	v_permlane32_swap_b32_e32 v34, v38
	v_permlane32_swap_b32_e32 v35, v39
	v_permlane32_swap_b32_e32 v40, v44
	v_permlane32_swap_b32_e32 v41, v45
	v_permlane32_swap_b32_e32 v42, v46
	v_permlane32_swap_b32_e32 v43, v47
	v_permlane32_swap_b32_e32 v16, v20
	v_permlane32_swap_b32_e32 v17, v21
	v_permlane32_swap_b32_e32 v18, v22
	v_permlane32_swap_b32_e32 v19, v23
	v_permlane32_swap_b32_e32 v24, v28
	v_permlane32_swap_b32_e32 v25, v29
	v_permlane32_swap_b32_e32 v26, v30
	v_permlane32_swap_b32_e32 v27, v31
	v_permlane32_swap_b32_e32 v0, v4
	v_permlane32_swap_b32_e32 v1, v5
	v_permlane32_swap_b32_e32 v2, v6
	v_permlane32_swap_b32_e32 v3, v7
	v_permlane32_swap_b32_e32 v8, v12
	v_permlane32_swap_b32_e32 v9, v13
	v_permlane32_swap_b32_e32 v10, v14
	v_permlane32_swap_b32_e32 v11, v15
	s_nop 1
